# stack: early tile-1 loads in diff prologues + hand-written final rmsnorm with 2-row prefetch, on top of the batched diff epilogue
# baseline (speedup 1.0000x reference)
.LBB0_794:
	v_ashrrev_i32_e32 v144, 3, v34
	s_mov_b32 s11, s49
	v_ashrrev_i32_e32 v145, 31, v144
	v_lshlrev_b32_e32 v20, 3, v34
	v_lshl_add_u64 v[2:3], v[144:145], 0, s[10:11]
	v_mov_b64_e32 v[4:5], s[94:95]
	v_and_b32_e32 v1, 56, v20
	v_ashrrev_i32_e32 v146, 4, v34
	v_mad_u64_u32 v[4:5], s[2:3], v2, s60, v[4:5]
	v_lshlrev_b32_e32 v32, 1, v1
	v_mad_i32_i24 v5, v3, s60, v5
	v_mov_b32_e32 v33, v153
	v_ashrrev_i32_e32 v147, 31, v146
	v_lshl_add_u64 v[2:3], v[4:5], 0, v[32:33]
	v_lshl_add_u64 v[4:5], v[146:147], 0, s[10:11]
	v_mov_b64_e32 v[6:7], s[70:71]
	v_mad_u64_u32 v[6:7], s[2:3], v4, s60, v[6:7]
	v_and_b32_e32 v1, 0x78, v20
	v_mad_i32_i24 v7, v5, s60, v7
	s_mov_b32 s91, s49
	v_lshl_add_u64 v[4:5], v[6:7], 0, s[90:91]
	v_lshlrev_b32_e32 v148, 1, v1
	v_mov_b32_e32 v149, v153
	v_lshl_add_u64 v[10:11], v[4:5], 0, v[148:149]
	s_mov_b64 s[100:101], 0x60000
	v_lshl_add_u64 v[244:245], v[2:3], 0, s[100:101]
	v_lshl_add_u64 v[246:247], v[10:11], 0, s[100:101]
	global_load_dwordx4 v[2:5], v[2:3], off offset:3072
	s_nop 0
	global_load_dwordx4 v[6:9], v[10:11], off
	v_add_co_u32_e32 v10, vcc, s58, v10
	v_and_b32_e32 v14, 0xfffff0, v146
	s_nop 0
	v_addc_co_u32_e32 v11, vcc, 0, v11, vcc
	global_load_dwordx4 v[10:13], v[10:11], off
	s_mov_b32 s100, s58
	s_mov_b32 s101, 0
	v_lshl_add_u64 v[248:249], v[246:247], 0, s[100:101]
	global_load_dwordx4 v[162:165], v[244:245], off offset:3072
	global_load_dwordx4 v[224:227], v[246:247], off
	global_load_dwordx4 v[232:235], v[248:249], off
	v_lshlrev_b32_e32 v15, 1, v146
	v_lshrrev_b32_e32 v16, 1, v146
	v_and_b32_e32 v18, 3, v146
	v_add_u32_e32 v21, 32, v146
	v_and_b32_e32 v1, 0x70, v34
	v_lshl_add_u32 v33, v0, 7, 0
	v_lshlrev_b32_e32 v0, 7, v144
	v_and_or_b32 v14, v15, 8, v14
	v_and_or_b32 v15, v16, 4, v18
	v_and_b32_e32 v16, 0xfffff0, v21
	v_lshlrev_b32_e32 v18, 1, v21
	v_bfe_u32 v17, v20, 5, 2
	v_bitop3_b32 v0, v32, v0, v1 bitop3:0xde
	v_lshrrev_b32_e32 v1, 1, v14
	v_lshlrev_b32_e32 v14, 6, v15
	v_and_or_b32 v15, v18, 8, v16
	v_or_b32_e32 v1, v1, v17
	v_lshrrev_b32_e32 v15, 1, v15
	v_lshlrev_b32_e32 v35, 4, v34
	v_add_u32_e32 v209, 0, v0
	v_lshlrev_b32_e32 v0, 9, v1
	v_or_b32_e32 v1, v15, v17
	v_and_b32_e32 v19, 48, v35
	v_bitop3_b32 v22, v152, v20, s37 bitop3:0x78
	v_lshlrev_b32_e32 v1, 9, v1
	v_add_u32_e32 v207, v33, v22
	v_or3_b32 v0, v0, v14, v19
	v_or3_b32 v1, v1, v14, v19
	v_add_u32_e32 v210, 0, v0
	v_add_u32_e32 v211, 0, v1
	v_and_b32_e32 v40, 0x70, v20
	v_bitop3_b32 v20, v152, v40, 32 bitop3:0x36
	v_add_u32_e32 v208, v33, v20
	v_bitop3_b32 v41, v152, v40, 64 bitop3:0x36
	v_add_u32_e32 v213, v33, v41
	v_bitop3_b32 v40, v152, v40, s88 bitop3:0x36
	v_add_u32_e32 v212, v33, v40
	s_waitcnt vmcnt(5)
	ds_write_b128 v209, v[2:5] offset:32768
	s_waitcnt vmcnt(4)
	ds_write_b128 v210, v[6:9]
	s_waitcnt vmcnt(3)
	ds_write_b128 v211, v[10:13]
	s_waitcnt lgkmcnt(0)
	s_barrier
	ds_read_b128 v[0:3], v207 offset:32768
	ds_read_b128 v[16:19], v207 offset:36864
	ds_read_b128 v[36:39], v208 offset:32768
	s_waitcnt lgkmcnt(2)
	v_mfma_f32_32x32x16_bf16 v[0:15], v[0:3], v[140:143], 0
	s_waitcnt lgkmcnt(0)
	v_mfma_f32_32x32x16_bf16 v[0:15], v[36:39], v[136:139], v[0:15]
	ds_read_b128 v[36:39], v208 offset:36864
	v_mfma_f32_32x32x16_bf16 v[16:31], v[16:19], v[140:143], 0
	s_waitcnt lgkmcnt(0)
	v_mfma_f32_32x32x16_bf16 v[16:31], v[36:39], v[136:139], v[16:31]
	ds_read_b128 v[36:39], v213 offset:32768
	s_waitcnt lgkmcnt(0)
	v_mfma_f32_32x32x16_bf16 v[0:15], v[36:39], v[132:135], v[0:15]
	ds_read_b128 v[36:39], v213 offset:36864
	s_waitcnt lgkmcnt(0)
	v_mfma_f32_32x32x16_bf16 v[16:31], v[36:39], v[132:135], v[16:31]
	ds_read_b128 v[36:39], v212 offset:32768
	s_waitcnt lgkmcnt(0)
	v_mfma_f32_32x32x16_bf16 v[0:15], v[36:39], v[128:131], v[0:15]
	ds_read_b128 v[36:39], v212 offset:36864
	s_waitcnt lgkmcnt(0)
	v_mfma_f32_32x32x16_bf16 v[16:31], v[36:39], v[128:131], v[16:31]
	s_nop 8
	v_max_f32_e32 v33, v1, v1
	v_max_f32_e32 v36, v0, v0
	v_max_f32_e32 v33, v36, v33
	v_max3_f32 v33, v33, v2, v3
	v_max3_f32 v33, v33, v4, v5
	v_max3_f32 v33, v33, v6, v7
	v_max3_f32 v33, v33, v8, v9
	v_max3_f32 v33, v33, v10, v11
	v_max3_f32 v33, v33, v12, v13
	v_max3_f32 v33, v33, v14, v15
	v_max3_f32 v33, v33, v16, v17
	v_max3_f32 v33, v33, v18, v19
	v_max3_f32 v33, v33, v20, v21
	v_max3_f32 v33, v33, v22, v23
	v_max3_f32 v33, v33, v24, v25
	v_max3_f32 v33, v33, v26, v27
	v_max3_f32 v33, v33, v28, v29
	v_max3_f32 v33, v33, v30, v31
	v_mov_b32_e32 v36, v33
	s_nop 1
	v_permlane32_swap_b32_e32 v33, v36
	v_max_f32_e32 v36, v36, v36
	v_max_f32_e32 v33, v33, v33
	v_max_f32_e32 v33, v33, v36
	v_add_f32_e32 v36, 0x7149f2ca, v33
	v_cmp_ge_f32_e32 vcc, s66, v36
	s_cmp_eq_u64 vcc, exec
	s_cbranch_scc0 .LBB0_863
	v_mov_b32_e32 v36, 0xf149f2ca
	v_mov_b32_e32 v214, 1.0
.LBB0_796:
	s_xor_b64 s[6:7], s[0:1], -1
	s_lshl_b32 s0, s9, 3
	s_or_b32 s18, s0, 0x8000
	s_cmp_lg_u32 0, -1
	s_cselect_b32 s2, 0, 0
	s_or_b32 s12, s10, 64
	s_mov_b32 s13, s11
	v_lshl_add_u64 v[38:39], s[12:13], 0, v[144:145]
	v_mov_b64_e32 v[40:41], s[94:95]
	v_mad_u64_u32 v[40:41], s[0:1], v38, s60, v[40:41]
	v_mad_i32_i24 v41, v39, s60, v41
	v_mov_b32_e32 v33, v153
	v_lshl_add_u64 v[38:39], v[40:41], 0, v[32:33]
	v_lshl_add_u64 v[40:41], s[12:13], 0, v[146:147]
	v_mov_b64_e32 v[42:43], s[70:71]
	v_mad_u64_u32 v[42:43], s[0:1], v40, s60, v[42:43]
	v_mad_i32_i24 v43, v41, s60, v43
	v_xor_b32_e32 v64, 0x80000000, v36
	v_lshl_add_u64 v[40:41], v[42:43], 0, s[90:91]
	v_mov_b32_e32 v149, v153
	v_mov_b32_e32 v65, v64
	v_mov_b32_e32 v66, v64
	v_mov_b32_e32 v67, v64
	v_mov_b32_e32 v68, v64
	v_mov_b32_e32 v69, v64
	v_mov_b32_e32 v70, v64
	v_mov_b32_e32 v71, v64
	v_mov_b32_e32 v72, v64
	v_mov_b32_e32 v73, v64
	v_mov_b32_e32 v74, v64
	v_mov_b32_e32 v75, v64
	v_mov_b32_e32 v76, v64
	v_mov_b32_e32 v77, v64
	v_mov_b32_e32 v78, v64
	v_mov_b32_e32 v79, v64
	v_lshl_add_u64 v[46:47], v[40:41], 0, v[148:149]
	s_nop 0
	v_add_co_u32_e32 v46, vcc, s58, v46
	v_sub_f32_e32 v0, v0, v36
	s_nop 0
	v_addc_co_u32_e32 v47, vcc, 0, v47, vcc
	v_exp_f32_e32 v183, v0
	v_sub_f32_e32 v0, v1, v36
	v_exp_f32_e32 v168, v0
	v_sub_f32_e32 v0, v2, v36
	v_exp_f32_e32 v185, v0
	v_sub_f32_e32 v0, v3, v36
	v_exp_f32_e32 v166, v0
	v_sub_f32_e32 v0, v4, v36
	v_exp_f32_e32 v186, v0
	v_sub_f32_e32 v0, v5, v36
	v_exp_f32_e32 v172, v0
	v_sub_f32_e32 v0, v6, v36
	v_exp_f32_e32 v187, v0
	v_sub_f32_e32 v0, v7, v36
	v_exp_f32_e32 v170, v0
	v_sub_f32_e32 v0, v8, v36
	v_exp_f32_e32 v176, v0
	v_sub_f32_e32 v0, v9, v36
	v_exp_f32_e32 v177, v0
	v_sub_f32_e32 v0, v10, v36
	v_exp_f32_e32 v174, v0
	v_sub_f32_e32 v0, v11, v36
	v_exp_f32_e32 v175, v0
	v_sub_f32_e32 v0, v12, v36
	v_exp_f32_e32 v180, v0
	v_sub_f32_e32 v0, v13, v36
	v_and_b32_e32 v203, 63, v34
	v_exp_f32_e32 v181, v0
	v_sub_f32_e32 v0, v14, v36
	v_lshlrev_b32_e32 v37, 3, v203
	v_and_b32_e32 v35, 0xc0, v35
	v_lshlrev_b32_e32 v34, 1, v34
	v_exp_f32_e32 v178, v0
	v_sub_f32_e32 v0, v15, v36
	v_and_or_b32 v35, v37, 24, v35
	v_and_b32_e32 v34, 32, v34
	v_and_b32_e32 v37, 0x100, v37
	v_exp_f32_e32 v179, v0
	v_or3_b32 v34, v35, v34, v37
	v_add_u32_e32 v206, s2, v34
	s_addk_i32 s2, 0x4000
	v_mov_b32_e32 v204, 0
	v_sub_f32_e32 v95, v31, v36
	v_sub_f32_e32 v94, v30, v36
	v_sub_f32_e32 v93, v29, v36
	v_sub_f32_e32 v92, v28, v36
	v_sub_f32_e32 v91, v27, v36
	v_sub_f32_e32 v90, v26, v36
	v_sub_f32_e32 v89, v25, v36
	v_sub_f32_e32 v88, v24, v36
	v_sub_f32_e32 v87, v23, v36
	v_sub_f32_e32 v86, v22, v36
	v_sub_f32_e32 v85, v21, v36
	v_sub_f32_e32 v84, v20, v36
	v_sub_f32_e32 v83, v19, v36
	v_sub_f32_e32 v82, v18, v36
	v_sub_f32_e32 v81, v17, v36
	v_sub_f32_e32 v80, v16, v36
	s_waitcnt vmcnt(2)
	ds_write_b128 v209, v[162:165] offset:40960
	s_waitcnt vmcnt(1)
	ds_write_b128 v210, v[224:227] offset:16384
	s_waitcnt vmcnt(0)
	ds_write_b128 v211, v[232:235] offset:16384
	v_add_u32_e32 v205, s2, v34
	v_lshl_add_u64 v[150:151], s[94:95], 0, v[32:33]
	s_mov_b64 s[14:15], 0
	s_movk_i32 s9, 0x80
	s_mov_b32 s16, 2
	v_readfirstlane_b32 s100, v239
	s_add_i32 s48, s10, 0x80
	v_lshl_add_u64 v[244:245], s[48:49], 0, v[144:145]
	v_mad_u64_u32 v[246:247], s[0:1], v244, s60, v[150:151]
	v_mad_i32_i24 v247, v245, s60, v247
	v_lshl_add_u64 v[244:245], s[48:49], 0, v[146:147]
	v_mov_b64_e32 v[248:249], s[70:71]
	global_load_dwordx4 v[162:165], v[246:247], off offset:3072
	v_mad_u64_u32 v[246:247], s[0:1], v244, s60, v[248:249]
	v_mad_i32_i24 v247, v245, s60, v247
	s_mov_b32 s91, s49
	v_lshl_add_u64 v[244:245], v[246:247], 0, s[90:91]
	v_lshl_add_u64 v[244:245], v[244:245], 0, v[148:149]
	s_mov_b32 s0, s58
	s_mov_b32 s1, 0
	v_lshl_add_u64 v[246:247], v[244:245], 0, s[0:1]
	global_load_dwordx4 v[224:227], v[244:245], off
	global_load_dwordx4 v[232:235], v[246:247], off
	v_mov_b32_e32 v0, 0
	v_mov_b32_e32 v1, v204
	v_mov_b32_e32 v2, v204
	v_mov_b32_e32 v3, v204
	v_mov_b32_e32 v4, v204
	v_mov_b32_e32 v5, v204
	v_mov_b32_e32 v6, v204
	v_mov_b32_e32 v7, v204
	v_mov_b32_e32 v8, v204
	v_mov_b32_e32 v9, v204
	v_mov_b32_e32 v10, v204
	v_mov_b32_e32 v11, v204
	v_mov_b32_e32 v12, v204
	v_mov_b32_e32 v13, v204
	v_mov_b32_e32 v14, v204
	v_mov_b32_e32 v15, v204
	v_mov_b32_e32 v16, 0
	v_mov_b32_e32 v17, v204
	v_mov_b32_e32 v18, v204
	v_mov_b32_e32 v19, v204
	v_mov_b32_e32 v20, v204
	v_mov_b32_e32 v21, v204
	v_mov_b32_e32 v22, v204
	v_mov_b32_e32 v23, v204
	v_mov_b32_e32 v24, v204
	v_mov_b32_e32 v25, v204
	v_mov_b32_e32 v26, v204
	v_mov_b32_e32 v27, v204
	v_mov_b32_e32 v28, v204
	v_mov_b32_e32 v29, v204
	v_mov_b32_e32 v30, v204
	v_mov_b32_e32 v31, v204
	v_mov_b32_e32 v32, 0
	v_mov_b32_e32 v33, v204
	v_mov_b32_e32 v34, v204
	v_mov_b32_e32 v35, v204
	v_mov_b32_e32 v36, v204
	v_mov_b32_e32 v37, v204
	v_mov_b32_e32 v38, v204
	v_mov_b32_e32 v39, v204
	v_mov_b32_e32 v40, v204
	v_mov_b32_e32 v41, v204
	v_mov_b32_e32 v42, v204
	v_mov_b32_e32 v43, v204
	v_mov_b32_e32 v44, v204
	v_mov_b32_e32 v45, v204
	v_mov_b32_e32 v46, v204
	v_mov_b32_e32 v47, v204
	v_mov_b32_e32 v48, 0
	v_mov_b32_e32 v49, v204
	v_mov_b32_e32 v50, v204
	v_mov_b32_e32 v51, v204
	v_mov_b32_e32 v52, v204
	v_mov_b32_e32 v53, v204
	v_mov_b32_e32 v54, v204
	v_mov_b32_e32 v55, v204
	v_mov_b32_e32 v56, v204
	v_mov_b32_e32 v57, v204
	v_mov_b32_e32 v58, v204
	v_mov_b32_e32 v59, v204
	v_mov_b32_e32 v60, v204
	v_mov_b32_e32 v61, v204
	v_mov_b32_e32 v62, v204
	v_mov_b32_e32 v63, v204
	s_waitcnt lgkmcnt(0)
	s_barrier
	v_xor_b32_e32 v209, 0x10000, v209
	v_xor_b32_e32 v210, 0x10000, v210
	v_xor_b32_e32 v211, 0x10000, v211

.LBB0_831:
	v_ashrrev_i32_e32 v184, 3, v34
	v_ashrrev_i32_e32 v185, 31, v184
	v_lshlrev_b32_e32 v20, 3, v34
	v_lshl_add_u64 v[2:3], v[184:185], 0, s[10:11]
	v_mov_b64_e32 v[4:5], s[94:95]
	v_and_b32_e32 v1, 56, v20
	v_ashrrev_i32_e32 v186, 4, v34
	v_mad_u64_u32 v[4:5], s[2:3], v2, s60, v[4:5]
	v_lshlrev_b32_e32 v32, 1, v1
	v_mad_i32_i24 v5, v3, s60, v5
	v_mov_b32_e32 v33, v153
	v_ashrrev_i32_e32 v187, 31, v186
	v_lshl_add_u64 v[2:3], v[4:5], 0, v[32:33]
	v_lshl_add_u64 v[4:5], v[186:187], 0, s[10:11]
	v_mov_b64_e32 v[6:7], s[70:71]
	v_mad_u64_u32 v[6:7], s[2:3], v4, s60, v[6:7]
	v_and_b32_e32 v1, 0x78, v20
	v_mad_i32_i24 v7, v5, s60, v7
	s_mov_b32 s91, s49
	v_lshl_add_u64 v[4:5], v[6:7], 0, s[90:91]
	v_lshlrev_b32_e32 v188, 1, v1
	v_mov_b32_e32 v189, v153
	v_lshl_add_u64 v[10:11], v[4:5], 0, v[188:189]
	s_mov_b64 s[100:101], 0x60000
	v_lshl_add_u64 v[178:179], v[2:3], 0, s[100:101]
	v_lshl_add_u64 v[180:181], v[10:11], 0, s[100:101]
	global_load_dwordx4 v[2:5], v[2:3], off offset:3200
	s_nop 0
	global_load_dwordx4 v[6:9], v[10:11], off
	v_add_co_u32_e32 v10, vcc, s58, v10
	v_and_b32_e32 v14, 0xfffff0, v186
	s_nop 0
	v_addc_co_u32_e32 v11, vcc, 0, v11, vcc
	global_load_dwordx4 v[10:13], v[10:11], off
	s_mov_b32 s100, s58
	s_mov_b32 s101, 0
	v_lshl_add_u64 v[182:183], v[180:181], 0, s[100:101]
	global_load_dwordx4 v[166:169], v[178:179], off offset:3200
	global_load_dwordx4 v[170:173], v[180:181], off
	global_load_dwordx4 v[174:177], v[182:183], off
	v_lshlrev_b32_e32 v15, 1, v186
	v_lshrrev_b32_e32 v16, 1, v186
	v_and_b32_e32 v18, 3, v186
	v_add_u32_e32 v21, 32, v186
	v_and_b32_e32 v1, 0x70, v34
	v_lshl_add_u32 v33, v0, 7, 0
	v_lshlrev_b32_e32 v0, 7, v184
	v_and_or_b32 v14, v15, 8, v14
	v_and_or_b32 v15, v16, 4, v18
	v_and_b32_e32 v16, 0xfffff0, v21
	v_lshlrev_b32_e32 v18, 1, v21
	v_bfe_u32 v17, v20, 5, 2
	v_bitop3_b32 v0, v32, v0, v1 bitop3:0xde
	v_lshrrev_b32_e32 v1, 1, v14
	v_lshlrev_b32_e32 v14, 6, v15
	v_and_or_b32 v15, v18, 8, v16
	v_or_b32_e32 v1, v1, v17
	v_lshrrev_b32_e32 v15, 1, v15
	v_lshlrev_b32_e32 v35, 4, v34
	v_add_u32_e32 v251, 0, v0
	v_lshlrev_b32_e32 v0, 9, v1
	v_or_b32_e32 v1, v15, v17
	v_and_b32_e32 v19, 48, v35
	v_bitop3_b32 v22, v152, v20, s37 bitop3:0x78
	v_lshlrev_b32_e32 v1, 9, v1
	v_add_u32_e32 v249, v33, v22
	v_or3_b32 v0, v0, v14, v19
	v_or3_b32 v1, v1, v14, v19
	v_add_u32_e32 v252, 0, v0
	v_add_u32_e32 v231, 0, v1
	v_and_b32_e32 v40, 0x70, v20
	v_bitop3_b32 v20, v152, v40, 32 bitop3:0x36
	v_add_u32_e32 v250, v33, v20
	v_bitop3_b32 v41, v152, v40, 64 bitop3:0x36
	v_add_u32_e32 v233, v33, v41
	v_bitop3_b32 v40, v152, v40, s88 bitop3:0x36
	v_add_u32_e32 v232, v33, v40
	s_waitcnt vmcnt(5)
	ds_write_b128 v251, v[2:5] offset:32768
	s_waitcnt vmcnt(4)
	ds_write_b128 v252, v[6:9]
	s_waitcnt vmcnt(3)
	ds_write_b128 v231, v[10:13]
	s_waitcnt lgkmcnt(0)
	s_barrier
	ds_read_b128 v[0:3], v249 offset:32768
	ds_read_b128 v[16:19], v249 offset:36864
	ds_read_b128 v[36:39], v250 offset:32768
	s_waitcnt lgkmcnt(2)
	v_mfma_f32_32x32x16_bf16 v[0:15], v[0:3], v[140:143], 0
	s_waitcnt lgkmcnt(0)
	v_mfma_f32_32x32x16_bf16 v[0:15], v[36:39], v[136:139], v[0:15]
	ds_read_b128 v[36:39], v250 offset:36864
	v_mfma_f32_32x32x16_bf16 v[16:31], v[16:19], v[140:143], 0
	s_waitcnt lgkmcnt(0)
	v_mfma_f32_32x32x16_bf16 v[16:31], v[36:39], v[136:139], v[16:31]
	ds_read_b128 v[36:39], v233 offset:32768
	s_waitcnt lgkmcnt(0)
	v_mfma_f32_32x32x16_bf16 v[0:15], v[36:39], v[132:135], v[0:15]
	ds_read_b128 v[36:39], v233 offset:36864
	s_waitcnt lgkmcnt(0)
	v_mfma_f32_32x32x16_bf16 v[16:31], v[36:39], v[132:135], v[16:31]
	ds_read_b128 v[36:39], v232 offset:32768
	s_waitcnt lgkmcnt(0)
	v_mfma_f32_32x32x16_bf16 v[0:15], v[36:39], v[128:131], v[0:15]
	ds_read_b128 v[36:39], v232 offset:36864
	s_waitcnt lgkmcnt(0)
	v_mfma_f32_32x32x16_bf16 v[16:31], v[36:39], v[128:131], v[16:31]
	s_nop 8
	v_max_f32_e32 v33, v1, v1
	v_max_f32_e32 v36, v0, v0
	v_max_f32_e32 v33, v36, v33
	v_max3_f32 v33, v33, v2, v3
	v_max3_f32 v33, v33, v4, v5
	v_max3_f32 v33, v33, v6, v7
	v_max3_f32 v33, v33, v8, v9
	v_max3_f32 v33, v33, v10, v11
	v_max3_f32 v33, v33, v12, v13
	v_max3_f32 v33, v33, v14, v15
	v_max3_f32 v33, v33, v16, v17
	v_max3_f32 v33, v33, v18, v19
	v_max3_f32 v33, v33, v20, v21
	v_max3_f32 v33, v33, v22, v23
	v_max3_f32 v33, v33, v24, v25
	v_max3_f32 v33, v33, v26, v27
	v_max3_f32 v33, v33, v28, v29
	v_max3_f32 v33, v33, v30, v31
	v_mov_b32_e32 v36, v33
	s_nop 1
	v_permlane32_swap_b32_e32 v33, v36
	v_max_f32_e32 v36, v36, v36
	v_max_f32_e32 v33, v33, v33
	v_max_f32_e32 v33, v33, v36
	v_add_f32_e32 v36, 0x7149f2ca, v33
	v_cmp_ge_f32_e32 vcc, s66, v36
	s_cmp_eq_u64 vcc, exec
	s_cbranch_scc0 .LBB0_864
	v_mov_b32_e32 v36, 0xf149f2ca
	v_mov_b32_e32 v234, 1.0
.LBB0_833:
	v_lshl_add_u64 v[38:39], s[12:13], 0, v[184:185]
	v_mov_b64_e32 v[40:41], s[94:95]
	v_mad_u64_u32 v[40:41], s[2:3], v38, s60, v[40:41]
	v_mad_i32_i24 v41, v39, s60, v41
	v_mov_b32_e32 v33, v153
	v_lshl_add_u64 v[38:39], v[40:41], 0, v[32:33]
	v_lshl_add_u64 v[40:41], s[12:13], 0, v[186:187]
	v_mov_b64_e32 v[42:43], s[70:71]
	v_mad_u64_u32 v[42:43], s[2:3], v40, s60, v[42:43]
	v_mad_i32_i24 v43, v41, s60, v43
	v_xor_b32_e32 v64, 0x80000000, v36
	v_lshl_add_u64 v[40:41], v[42:43], 0, s[90:91]
	v_mov_b32_e32 v189, v153
	v_mov_b32_e32 v65, v64
	v_mov_b32_e32 v66, v64
	v_mov_b32_e32 v67, v64
	v_mov_b32_e32 v68, v64
	v_mov_b32_e32 v69, v64
	v_mov_b32_e32 v70, v64
	v_mov_b32_e32 v71, v64
	v_mov_b32_e32 v72, v64
	v_mov_b32_e32 v73, v64
	v_mov_b32_e32 v74, v64
	v_mov_b32_e32 v75, v64
	v_mov_b32_e32 v76, v64
	v_mov_b32_e32 v77, v64
	v_mov_b32_e32 v78, v64
	v_mov_b32_e32 v79, v64
	v_lshl_add_u64 v[46:47], v[40:41], 0, v[188:189]
	s_nop 0
	v_add_co_u32_e32 v46, vcc, s58, v46
	v_sub_f32_e32 v0, v0, v36
	s_nop 0
	v_addc_co_u32_e32 v47, vcc, 0, v47, vcc
	v_exp_f32_e32 v209, v0
	v_sub_f32_e32 v0, v1, v36
	v_exp_f32_e32 v194, v0
	v_sub_f32_e32 v0, v2, v36
	v_exp_f32_e32 v211, v0
	v_sub_f32_e32 v0, v3, v36
	v_exp_f32_e32 v192, v0
	v_sub_f32_e32 v0, v4, v36
	s_mov_b64 s[2:3], 0x1000
	v_exp_f32_e32 v212, v0
	v_sub_f32_e32 v0, v5, v36
	s_mov_b64 s[2:3], 0x1400
	v_exp_f32_e32 v198, v0
	v_sub_f32_e32 v0, v6, v36
	s_mov_b64 s[2:3], 0x1800
	v_exp_f32_e32 v213, v0
	v_sub_f32_e32 v0, v7, v36
	s_mov_b64 s[2:3], 0x1c00
	v_exp_f32_e32 v196, v0
	v_sub_f32_e32 v0, v8, v36
	s_mov_b64 s[2:3], 0x2000
	v_exp_f32_e32 v202, v0
	v_sub_f32_e32 v0, v9, v36
	s_mov_b64 s[2:3], 0x2400
	v_exp_f32_e32 v203, v0
	v_sub_f32_e32 v0, v10, v36
	s_mov_b64 s[2:3], 0x2800
	v_exp_f32_e32 v200, v0
	v_sub_f32_e32 v0, v11, v36
	s_mov_b64 s[2:3], 0x2c00
	v_exp_f32_e32 v201, v0
	v_sub_f32_e32 v0, v12, v36
	s_mov_b64 s[2:3], 0x3000
	v_exp_f32_e32 v206, v0
	v_sub_f32_e32 v0, v13, v36
	s_mov_b64 s[2:3], 0x3400
	v_and_b32_e32 v245, 63, v34
	v_exp_f32_e32 v207, v0
	v_sub_f32_e32 v0, v14, v36
	s_mov_b64 s[2:3], 0x3800
	v_lshlrev_b32_e32 v37, 3, v245
	v_and_b32_e32 v35, 0xc0, v35
	v_lshlrev_b32_e32 v34, 1, v34
	v_exp_f32_e32 v204, v0
	v_sub_f32_e32 v0, v15, v36
	s_mov_b64 s[2:3], 0x3c00
	v_and_or_b32 v35, v37, 24, v35
	v_and_b32_e32 v34, 32, v34
	v_and_b32_e32 v37, 0x100, v37
	s_cmp_lg_u32 0, -1
	v_exp_f32_e32 v205, v0
	v_or3_b32 v34, v35, v34, v37
	s_cselect_b32 s2, 0, 0
	v_add_u32_e32 v248, s2, v34
	s_addk_i32 s2, 0x4000
	v_mov_b32_e32 v246, 0
	v_sub_f32_e32 v95, v31, v36
	v_sub_f32_e32 v94, v30, v36
	v_sub_f32_e32 v93, v29, v36
	v_sub_f32_e32 v92, v28, v36
	v_sub_f32_e32 v91, v27, v36
	v_sub_f32_e32 v90, v26, v36
	v_sub_f32_e32 v89, v25, v36
	v_sub_f32_e32 v88, v24, v36
	v_sub_f32_e32 v87, v23, v36
	v_sub_f32_e32 v86, v22, v36
	v_sub_f32_e32 v85, v21, v36
	v_sub_f32_e32 v84, v20, v36
	v_sub_f32_e32 v83, v19, v36
	v_sub_f32_e32 v82, v18, v36
	v_sub_f32_e32 v81, v17, v36
	v_sub_f32_e32 v80, v16, v36
	s_waitcnt vmcnt(2)
	ds_write_b128 v251, v[166:169] offset:40960
	s_waitcnt vmcnt(1)
	ds_write_b128 v252, v[170:173] offset:16384
	s_waitcnt vmcnt(0)
	ds_write_b128 v231, v[174:177] offset:16384
	v_add_u32_e32 v247, s2, v34
	v_lshl_add_u64 v[190:191], s[94:95], 0, v[32:33]
	s_mov_b64 s[16:17], 0
	s_movk_i32 s19, 0x80
	s_mov_b32 s21, 2
	s_add_i32 s48, s10, 0x80
	v_lshl_add_u64 v[178:179], s[48:49], 0, v[184:185]
	v_mad_u64_u32 v[180:181], s[100:101], v178, s60, v[190:191]
	v_mad_i32_i24 v181, v179, s60, v181
	v_lshl_add_u64 v[178:179], s[48:49], 0, v[186:187]
	v_mov_b64_e32 v[182:183], s[70:71]
	global_load_dwordx4 v[166:169], v[180:181], off offset:3200
	v_mad_u64_u32 v[180:181], s[100:101], v178, s60, v[182:183]
	v_mad_i32_i24 v181, v179, s60, v181
	s_mov_b32 s91, s49
	v_lshl_add_u64 v[178:179], v[180:181], 0, s[90:91]
	v_lshl_add_u64 v[178:179], v[178:179], 0, v[188:189]
	s_mov_b32 s100, s58
	s_mov_b32 s101, 0
	v_lshl_add_u64 v[180:181], v[178:179], 0, s[100:101]
	global_load_dwordx4 v[170:173], v[178:179], off
	global_load_dwordx4 v[174:177], v[180:181], off
	v_mov_b32_e32 v0, 0
	v_mov_b32_e32 v1, v246
	v_mov_b32_e32 v2, v246
	v_mov_b32_e32 v3, v246
	v_mov_b32_e32 v4, v246
	v_mov_b32_e32 v5, v246
	v_mov_b32_e32 v6, v246
	v_mov_b32_e32 v7, v246
	v_mov_b32_e32 v8, v246
	v_mov_b32_e32 v9, v246
	v_mov_b32_e32 v10, v246
	v_mov_b32_e32 v11, v246
	v_mov_b32_e32 v12, v246
	v_mov_b32_e32 v13, v246
	v_mov_b32_e32 v14, v246
	v_mov_b32_e32 v15, v246
	v_mov_b32_e32 v16, 0
	v_mov_b32_e32 v17, v246
	v_mov_b32_e32 v18, v246
	v_mov_b32_e32 v19, v246
	v_mov_b32_e32 v20, v246
	v_mov_b32_e32 v21, v246
	v_mov_b32_e32 v22, v246
	v_mov_b32_e32 v23, v246
	v_mov_b32_e32 v24, v246
	v_mov_b32_e32 v25, v246
	v_mov_b32_e32 v26, v246
	v_mov_b32_e32 v27, v246
	v_mov_b32_e32 v28, v246
	v_mov_b32_e32 v29, v246
	v_mov_b32_e32 v30, v246
	v_mov_b32_e32 v31, v246
	v_mov_b32_e32 v32, 0
	v_mov_b32_e32 v33, v246
	v_mov_b32_e32 v34, v246
	v_mov_b32_e32 v35, v246
	v_mov_b32_e32 v36, v246
	v_mov_b32_e32 v37, v246
	v_mov_b32_e32 v38, v246
	v_mov_b32_e32 v39, v246
	v_mov_b32_e32 v40, v246
	v_mov_b32_e32 v41, v246
	v_mov_b32_e32 v42, v246
	v_mov_b32_e32 v43, v246
	v_mov_b32_e32 v44, v246
	v_mov_b32_e32 v45, v246
	v_mov_b32_e32 v46, v246
	v_mov_b32_e32 v47, v246
	v_mov_b32_e32 v48, 0
	v_mov_b32_e32 v49, v246
	v_mov_b32_e32 v50, v246
	v_mov_b32_e32 v51, v246
	v_mov_b32_e32 v52, v246
	v_mov_b32_e32 v53, v246
	v_mov_b32_e32 v54, v246
	v_mov_b32_e32 v55, v246
	v_mov_b32_e32 v56, v246
	v_mov_b32_e32 v57, v246
	v_mov_b32_e32 v58, v246
	v_mov_b32_e32 v59, v246
	v_mov_b32_e32 v60, v246
	v_mov_b32_e32 v61, v246
	v_mov_b32_e32 v62, v246
	v_mov_b32_e32 v63, v246
	s_waitcnt lgkmcnt(0)
	s_barrier
	v_xor_b32_e32 v251, 0x10000, v251
	v_xor_b32_e32 v252, 0x10000, v252
	v_xor_b32_e32 v231, 0x10000, v231

.LBB0_1422:
	v_mbcnt_lo_u32_b32 v0, -1, 0
	v_mbcnt_hi_u32_b32 v0, -1, v0
	s_nop 0
	v_add_u32_e32 v16, s33, v0
	s_nop 0
	v_readfirstlane_b32 s0, v16
	s_ashr_i32 s1, s0, 6
	v_readlane_b32 s0, v253, 47
	s_add_i32 s0, s1, s0
	s_cmpk_gt_i32 s0, 0x7fff
	s_cbranch_scc1 .LBB0_1425
	v_lshlrev_b32_e32 v0, 4, v16
	v_and_b32_e32 v17, 0x3f0, v0
	global_load_dwordx4 v[0:3], v17, s[72:73]
	global_load_dwordx4 v[4:7], v17, s[72:73] offset:1024
	global_load_dwordx4 v[8:11], v17, s[72:73] offset:2048
	global_load_dwordx4 v[12:15], v17, s[72:73] offset:3072
	v_mov_b32_e32 v100, v17
	s_mov_b32 s4, s0
	s_mov_b32 s5, 0
	s_lshl_b64 s[6:7], s[4:5], 12
	s_add_u32 s6, s74, s6
	s_addc_u32 s7, s75, s7
	s_mov_b64 s[8:9], s[6:7]
	v_mov_b32_e32 v74, 0x358637bd
	v_mov_b32_e32 v73, 0
	global_load_dwordx4 v[20:23], v100, s[6:7]
	global_load_dwordx4 v[24:27], v100, s[6:7] offset:1024
	global_load_dwordx4 v[28:31], v100, s[6:7] offset:2048
	global_load_dwordx4 v[32:35], v100, s[6:7] offset:3072
	s_add_u32 s6, s6, 0x800000
	s_addc_u32 s7, s7, 0
	global_load_dwordx4 v[36:39], v100, s[6:7]
	global_load_dwordx4 v[40:43], v100, s[6:7] offset:1024
	global_load_dwordx4 v[44:47], v100, s[6:7] offset:2048
	global_load_dwordx4 v[48:51], v100, s[6:7] offset:3072
	s_add_u32 s6, s6, 0x800000
	s_addc_u32 s7, s7, 0
	global_load_dwordx4 v[52:55], v100, s[6:7]
	global_load_dwordx4 v[56:59], v100, s[6:7] offset:1024
	global_load_dwordx4 v[60:63], v100, s[6:7] offset:2048
	global_load_dwordx4 v[64:67], v100, s[6:7] offset:3072
	s_add_u32 s6, s6, 0x800000
	s_addc_u32 s7, s7, 0
	s_waitcnt vmcnt(8)
	v_pk_mul_f32 v[68:69], v[20:21], v[20:21]
	v_pk_fma_f32 v[68:69], v[22:23], v[22:23], v[68:69]
	v_pk_fma_f32 v[68:69], v[24:25], v[24:25], v[68:69]
	v_pk_fma_f32 v[68:69], v[26:27], v[26:27], v[68:69]
	v_pk_fma_f32 v[68:69], v[28:29], v[28:29], v[68:69]
	v_pk_fma_f32 v[68:69], v[30:31], v[30:31], v[68:69]
	v_pk_fma_f32 v[68:69], v[32:33], v[32:33], v[68:69]
	v_pk_fma_f32 v[68:69], v[34:35], v[34:35], v[68:69]
	v_add_f32_e32 v70, v68, v69
	s_nop 1
	v_add_f32_dpp v71, v70, v70 quad_perm:[1,0,3,2] row_mask:0xf bank_mask:0xf
	s_nop 1
	v_add_f32_dpp v70, v71, v71 quad_perm:[2,3,0,1] row_mask:0xf bank_mask:0xf
	s_nop 1
	v_add_f32_dpp v71, v70, v70 row_half_mirror row_mask:0xf bank_mask:0xf
	s_nop 1
	v_add_f32_dpp v70, v71, v71 row_mirror row_mask:0xf bank_mask:0xf
	v_mov_b32_e32 v71, v70
	s_nop 1
	v_add_f32_dpp v71, v70, v70 row_bcast:15 row_mask:0xa bank_mask:0xf
	s_nop 1
	v_mov_b32_e32 v70, v71
	s_nop 1
	v_add_f32_dpp v70, v71, v71 row_bcast:31 row_mask:0xc bank_mask:0xf
	s_nop 1
	v_readlane_b32 s16, v70, 63
	s_nop 1
	v_mov_b32_e32 v72, s16
	v_fmamk_f32 v72, v72, 0x3a800000, v74
	v_rsq_f32_e32 v72, v72
	s_nop 0
	v_pk_mul_f32 v[20:21], v[20:21], v[72:73] op_sel_hi:[1,0]
	v_pk_mul_f32 v[22:23], v[22:23], v[72:73] op_sel_hi:[1,0]
	v_pk_mul_f32 v[20:21], v[20:21], v[0:1]
	v_pk_mul_f32 v[22:23], v[22:23], v[2:3]
	global_store_dwordx4 v100, v[20:23], s[8:9]
	v_pk_mul_f32 v[24:25], v[24:25], v[72:73] op_sel_hi:[1,0]
	v_pk_mul_f32 v[26:27], v[26:27], v[72:73] op_sel_hi:[1,0]
	v_pk_mul_f32 v[24:25], v[24:25], v[4:5]
	v_pk_mul_f32 v[26:27], v[26:27], v[6:7]
	global_store_dwordx4 v100, v[24:27], s[8:9] offset:1024
	v_pk_mul_f32 v[28:29], v[28:29], v[72:73] op_sel_hi:[1,0]
	v_pk_mul_f32 v[30:31], v[30:31], v[72:73] op_sel_hi:[1,0]
	v_pk_mul_f32 v[28:29], v[28:29], v[8:9]
	v_pk_mul_f32 v[30:31], v[30:31], v[10:11]
	global_store_dwordx4 v100, v[28:31], s[8:9] offset:2048
	v_pk_mul_f32 v[32:33], v[32:33], v[72:73] op_sel_hi:[1,0]
	v_pk_mul_f32 v[34:35], v[34:35], v[72:73] op_sel_hi:[1,0]
	v_pk_mul_f32 v[32:33], v[32:33], v[12:13]
	v_pk_mul_f32 v[34:35], v[34:35], v[14:15]
	global_store_dwordx4 v100, v[32:35], s[8:9] offset:3072
	s_add_u32 s8, s8, 0x800000
	s_addc_u32 s9, s9, 0
	global_load_dwordx4 v[20:23], v100, s[6:7]
	global_load_dwordx4 v[24:27], v100, s[6:7] offset:1024
	global_load_dwordx4 v[28:31], v100, s[6:7] offset:2048
	global_load_dwordx4 v[32:35], v100, s[6:7] offset:3072
	s_add_u32 s6, s6, 0x800000
	s_addc_u32 s7, s7, 0
	s_waitcnt vmcnt(12)
	v_pk_mul_f32 v[68:69], v[36:37], v[36:37]
	v_pk_fma_f32 v[68:69], v[38:39], v[38:39], v[68:69]
	v_pk_fma_f32 v[68:69], v[40:41], v[40:41], v[68:69]
	v_pk_fma_f32 v[68:69], v[42:43], v[42:43], v[68:69]
	v_pk_fma_f32 v[68:69], v[44:45], v[44:45], v[68:69]
	v_pk_fma_f32 v[68:69], v[46:47], v[46:47], v[68:69]
	v_pk_fma_f32 v[68:69], v[48:49], v[48:49], v[68:69]
	v_pk_fma_f32 v[68:69], v[50:51], v[50:51], v[68:69]
	v_add_f32_e32 v70, v68, v69
	s_nop 1
	v_add_f32_dpp v71, v70, v70 quad_perm:[1,0,3,2] row_mask:0xf bank_mask:0xf
	s_nop 1
	v_add_f32_dpp v70, v71, v71 quad_perm:[2,3,0,1] row_mask:0xf bank_mask:0xf
	s_nop 1
	v_add_f32_dpp v71, v70, v70 row_half_mirror row_mask:0xf bank_mask:0xf
	s_nop 1
	v_add_f32_dpp v70, v71, v71 row_mirror row_mask:0xf bank_mask:0xf
	v_mov_b32_e32 v71, v70
	s_nop 1
	v_add_f32_dpp v71, v70, v70 row_bcast:15 row_mask:0xa bank_mask:0xf
	s_nop 1
	v_mov_b32_e32 v70, v71
	s_nop 1
	v_add_f32_dpp v70, v71, v71 row_bcast:31 row_mask:0xc bank_mask:0xf
	s_nop 1
	v_readlane_b32 s16, v70, 63
	s_nop 1
	v_mov_b32_e32 v72, s16
	v_fmamk_f32 v72, v72, 0x3a800000, v74
	v_rsq_f32_e32 v72, v72
	s_nop 0
	v_pk_mul_f32 v[36:37], v[36:37], v[72:73] op_sel_hi:[1,0]
	v_pk_mul_f32 v[38:39], v[38:39], v[72:73] op_sel_hi:[1,0]
	v_pk_mul_f32 v[36:37], v[36:37], v[0:1]
	v_pk_mul_f32 v[38:39], v[38:39], v[2:3]
	global_store_dwordx4 v100, v[36:39], s[8:9]
	v_pk_mul_f32 v[40:41], v[40:41], v[72:73] op_sel_hi:[1,0]
	v_pk_mul_f32 v[42:43], v[42:43], v[72:73] op_sel_hi:[1,0]
	v_pk_mul_f32 v[40:41], v[40:41], v[4:5]
	v_pk_mul_f32 v[42:43], v[42:43], v[6:7]
	global_store_dwordx4 v100, v[40:43], s[8:9] offset:1024
	v_pk_mul_f32 v[44:45], v[44:45], v[72:73] op_sel_hi:[1,0]
	v_pk_mul_f32 v[46:47], v[46:47], v[72:73] op_sel_hi:[1,0]
	v_pk_mul_f32 v[44:45], v[44:45], v[8:9]
	v_pk_mul_f32 v[46:47], v[46:47], v[10:11]
	global_store_dwordx4 v100, v[44:47], s[8:9] offset:2048
	v_pk_mul_f32 v[48:49], v[48:49], v[72:73] op_sel_hi:[1,0]
	v_pk_mul_f32 v[50:51], v[50:51], v[72:73] op_sel_hi:[1,0]
	v_pk_mul_f32 v[48:49], v[48:49], v[12:13]
	v_pk_mul_f32 v[50:51], v[50:51], v[14:15]
	global_store_dwordx4 v100, v[48:51], s[8:9] offset:3072
	s_add_u32 s8, s8, 0x800000
	s_addc_u32 s9, s9, 0
	global_load_dwordx4 v[36:39], v100, s[6:7]
	global_load_dwordx4 v[40:43], v100, s[6:7] offset:1024
	global_load_dwordx4 v[44:47], v100, s[6:7] offset:2048
	global_load_dwordx4 v[48:51], v100, s[6:7] offset:3072
	s_add_u32 s6, s6, 0x800000
	s_addc_u32 s7, s7, 0
	s_waitcnt vmcnt(16)
	v_pk_mul_f32 v[68:69], v[52:53], v[52:53]
	v_pk_fma_f32 v[68:69], v[54:55], v[54:55], v[68:69]
	v_pk_fma_f32 v[68:69], v[56:57], v[56:57], v[68:69]
	v_pk_fma_f32 v[68:69], v[58:59], v[58:59], v[68:69]
	v_pk_fma_f32 v[68:69], v[60:61], v[60:61], v[68:69]
	v_pk_fma_f32 v[68:69], v[62:63], v[62:63], v[68:69]
	v_pk_fma_f32 v[68:69], v[64:65], v[64:65], v[68:69]
	v_pk_fma_f32 v[68:69], v[66:67], v[66:67], v[68:69]
	v_add_f32_e32 v70, v68, v69
	s_nop 1
	v_add_f32_dpp v71, v70, v70 quad_perm:[1,0,3,2] row_mask:0xf bank_mask:0xf
	s_nop 1
	v_add_f32_dpp v70, v71, v71 quad_perm:[2,3,0,1] row_mask:0xf bank_mask:0xf
	s_nop 1
	v_add_f32_dpp v71, v70, v70 row_half_mirror row_mask:0xf bank_mask:0xf
	s_nop 1
	v_add_f32_dpp v70, v71, v71 row_mirror row_mask:0xf bank_mask:0xf
	v_mov_b32_e32 v71, v70
	s_nop 1
	v_add_f32_dpp v71, v70, v70 row_bcast:15 row_mask:0xa bank_mask:0xf
	s_nop 1
	v_mov_b32_e32 v70, v71
	s_nop 1
	v_add_f32_dpp v70, v71, v71 row_bcast:31 row_mask:0xc bank_mask:0xf
	s_nop 1
	v_readlane_b32 s16, v70, 63
	s_nop 1
	v_mov_b32_e32 v72, s16
	v_fmamk_f32 v72, v72, 0x3a800000, v74
	v_rsq_f32_e32 v72, v72
	s_nop 0
	v_pk_mul_f32 v[52:53], v[52:53], v[72:73] op_sel_hi:[1,0]
	v_pk_mul_f32 v[54:55], v[54:55], v[72:73] op_sel_hi:[1,0]
	v_pk_mul_f32 v[52:53], v[52:53], v[0:1]
	v_pk_mul_f32 v[54:55], v[54:55], v[2:3]
	global_store_dwordx4 v100, v[52:55], s[8:9]
	v_pk_mul_f32 v[56:57], v[56:57], v[72:73] op_sel_hi:[1,0]
	v_pk_mul_f32 v[58:59], v[58:59], v[72:73] op_sel_hi:[1,0]
	v_pk_mul_f32 v[56:57], v[56:57], v[4:5]
	v_pk_mul_f32 v[58:59], v[58:59], v[6:7]
	global_store_dwordx4 v100, v[56:59], s[8:9] offset:1024
	v_pk_mul_f32 v[60:61], v[60:61], v[72:73] op_sel_hi:[1,0]
	v_pk_mul_f32 v[62:63], v[62:63], v[72:73] op_sel_hi:[1,0]
	v_pk_mul_f32 v[60:61], v[60:61], v[8:9]
	v_pk_mul_f32 v[62:63], v[62:63], v[10:11]
	global_store_dwordx4 v100, v[60:63], s[8:9] offset:2048
	v_pk_mul_f32 v[64:65], v[64:65], v[72:73] op_sel_hi:[1,0]
	v_pk_mul_f32 v[66:67], v[66:67], v[72:73] op_sel_hi:[1,0]
	v_pk_mul_f32 v[64:65], v[64:65], v[12:13]
	v_pk_mul_f32 v[66:67], v[66:67], v[14:15]
	global_store_dwordx4 v100, v[64:67], s[8:9] offset:3072
	s_add_u32 s8, s8, 0x800000
	s_addc_u32 s9, s9, 0
	global_load_dwordx4 v[52:55], v100, s[6:7]
	global_load_dwordx4 v[56:59], v100, s[6:7] offset:1024
	global_load_dwordx4 v[60:63], v100, s[6:7] offset:2048
	global_load_dwordx4 v[64:67], v100, s[6:7] offset:3072
	s_add_u32 s6, s6, 0x800000
	s_addc_u32 s7, s7, 0
	s_waitcnt vmcnt(16)
	v_pk_mul_f32 v[68:69], v[20:21], v[20:21]
	v_pk_fma_f32 v[68:69], v[22:23], v[22:23], v[68:69]
	v_pk_fma_f32 v[68:69], v[24:25], v[24:25], v[68:69]
	v_pk_fma_f32 v[68:69], v[26:27], v[26:27], v[68:69]
	v_pk_fma_f32 v[68:69], v[28:29], v[28:29], v[68:69]
	v_pk_fma_f32 v[68:69], v[30:31], v[30:31], v[68:69]
	v_pk_fma_f32 v[68:69], v[32:33], v[32:33], v[68:69]
	v_pk_fma_f32 v[68:69], v[34:35], v[34:35], v[68:69]
	v_add_f32_e32 v70, v68, v69
	s_nop 1
	v_add_f32_dpp v71, v70, v70 quad_perm:[1,0,3,2] row_mask:0xf bank_mask:0xf
	s_nop 1
	v_add_f32_dpp v70, v71, v71 quad_perm:[2,3,0,1] row_mask:0xf bank_mask:0xf
	s_nop 1
	v_add_f32_dpp v71, v70, v70 row_half_mirror row_mask:0xf bank_mask:0xf
	s_nop 1
	v_add_f32_dpp v70, v71, v71 row_mirror row_mask:0xf bank_mask:0xf
	v_mov_b32_e32 v71, v70
	s_nop 1
	v_add_f32_dpp v71, v70, v70 row_bcast:15 row_mask:0xa bank_mask:0xf
	s_nop 1
	v_mov_b32_e32 v70, v71
	s_nop 1
	v_add_f32_dpp v70, v71, v71 row_bcast:31 row_mask:0xc bank_mask:0xf
	s_nop 1
	v_readlane_b32 s16, v70, 63
	s_nop 1
	v_mov_b32_e32 v72, s16
	v_fmamk_f32 v72, v72, 0x3a800000, v74
	v_rsq_f32_e32 v72, v72
	s_nop 0
	v_pk_mul_f32 v[20:21], v[20:21], v[72:73] op_sel_hi:[1,0]
	v_pk_mul_f32 v[22:23], v[22:23], v[72:73] op_sel_hi:[1,0]
	v_pk_mul_f32 v[20:21], v[20:21], v[0:1]
	v_pk_mul_f32 v[22:23], v[22:23], v[2:3]
	global_store_dwordx4 v100, v[20:23], s[8:9]
	v_pk_mul_f32 v[24:25], v[24:25], v[72:73] op_sel_hi:[1,0]
	v_pk_mul_f32 v[26:27], v[26:27], v[72:73] op_sel_hi:[1,0]
	v_pk_mul_f32 v[24:25], v[24:25], v[4:5]
	v_pk_mul_f32 v[26:27], v[26:27], v[6:7]
	global_store_dwordx4 v100, v[24:27], s[8:9] offset:1024
	v_pk_mul_f32 v[28:29], v[28:29], v[72:73] op_sel_hi:[1,0]
	v_pk_mul_f32 v[30:31], v[30:31], v[72:73] op_sel_hi:[1,0]
	v_pk_mul_f32 v[28:29], v[28:29], v[8:9]
	v_pk_mul_f32 v[30:31], v[30:31], v[10:11]
	global_store_dwordx4 v100, v[28:31], s[8:9] offset:2048
	v_pk_mul_f32 v[32:33], v[32:33], v[72:73] op_sel_hi:[1,0]
	v_pk_mul_f32 v[34:35], v[34:35], v[72:73] op_sel_hi:[1,0]
	v_pk_mul_f32 v[32:33], v[32:33], v[12:13]
	v_pk_mul_f32 v[34:35], v[34:35], v[14:15]
	global_store_dwordx4 v100, v[32:35], s[8:9] offset:3072
	s_add_u32 s8, s8, 0x800000
	s_addc_u32 s9, s9, 0
	global_load_dwordx4 v[20:23], v100, s[6:7]
	global_load_dwordx4 v[24:27], v100, s[6:7] offset:1024
	global_load_dwordx4 v[28:31], v100, s[6:7] offset:2048
	global_load_dwordx4 v[32:35], v100, s[6:7] offset:3072
	s_add_u32 s6, s6, 0x800000
	s_addc_u32 s7, s7, 0
	s_waitcnt vmcnt(16)
	v_pk_mul_f32 v[68:69], v[36:37], v[36:37]
	v_pk_fma_f32 v[68:69], v[38:39], v[38:39], v[68:69]
	v_pk_fma_f32 v[68:69], v[40:41], v[40:41], v[68:69]
	v_pk_fma_f32 v[68:69], v[42:43], v[42:43], v[68:69]
	v_pk_fma_f32 v[68:69], v[44:45], v[44:45], v[68:69]
	v_pk_fma_f32 v[68:69], v[46:47], v[46:47], v[68:69]
	v_pk_fma_f32 v[68:69], v[48:49], v[48:49], v[68:69]
	v_pk_fma_f32 v[68:69], v[50:51], v[50:51], v[68:69]
	v_add_f32_e32 v70, v68, v69
	s_nop 1
	v_add_f32_dpp v71, v70, v70 quad_perm:[1,0,3,2] row_mask:0xf bank_mask:0xf
	s_nop 1
	v_add_f32_dpp v70, v71, v71 quad_perm:[2,3,0,1] row_mask:0xf bank_mask:0xf
	s_nop 1
	v_add_f32_dpp v71, v70, v70 row_half_mirror row_mask:0xf bank_mask:0xf
	s_nop 1
	v_add_f32_dpp v70, v71, v71 row_mirror row_mask:0xf bank_mask:0xf
	v_mov_b32_e32 v71, v70
	s_nop 1
	v_add_f32_dpp v71, v70, v70 row_bcast:15 row_mask:0xa bank_mask:0xf
	s_nop 1
	v_mov_b32_e32 v70, v71
	s_nop 1
	v_add_f32_dpp v70, v71, v71 row_bcast:31 row_mask:0xc bank_mask:0xf
	s_nop 1
	v_readlane_b32 s16, v70, 63
	s_nop 1
	v_mov_b32_e32 v72, s16
	v_fmamk_f32 v72, v72, 0x3a800000, v74
	v_rsq_f32_e32 v72, v72
	s_nop 0
	v_pk_mul_f32 v[36:37], v[36:37], v[72:73] op_sel_hi:[1,0]
	v_pk_mul_f32 v[38:39], v[38:39], v[72:73] op_sel_hi:[1,0]
	v_pk_mul_f32 v[36:37], v[36:37], v[0:1]
	v_pk_mul_f32 v[38:39], v[38:39], v[2:3]
	global_store_dwordx4 v100, v[36:39], s[8:9]
	v_pk_mul_f32 v[40:41], v[40:41], v[72:73] op_sel_hi:[1,0]
	v_pk_mul_f32 v[42:43], v[42:43], v[72:73] op_sel_hi:[1,0]
	v_pk_mul_f32 v[40:41], v[40:41], v[4:5]
	v_pk_mul_f32 v[42:43], v[42:43], v[6:7]
	global_store_dwordx4 v100, v[40:43], s[8:9] offset:1024
	v_pk_mul_f32 v[44:45], v[44:45], v[72:73] op_sel_hi:[1,0]
	v_pk_mul_f32 v[46:47], v[46:47], v[72:73] op_sel_hi:[1,0]
	v_pk_mul_f32 v[44:45], v[44:45], v[8:9]
	v_pk_mul_f32 v[46:47], v[46:47], v[10:11]
	global_store_dwordx4 v100, v[44:47], s[8:9] offset:2048
	v_pk_mul_f32 v[48:49], v[48:49], v[72:73] op_sel_hi:[1,0]
	v_pk_mul_f32 v[50:51], v[50:51], v[72:73] op_sel_hi:[1,0]
	v_pk_mul_f32 v[48:49], v[48:49], v[12:13]
	v_pk_mul_f32 v[50:51], v[50:51], v[14:15]
	global_store_dwordx4 v100, v[48:51], s[8:9] offset:3072
	s_add_u32 s8, s8, 0x800000
	s_addc_u32 s9, s9, 0
	global_load_dwordx4 v[36:39], v100, s[6:7]
	global_load_dwordx4 v[40:43], v100, s[6:7] offset:1024
	global_load_dwordx4 v[44:47], v100, s[6:7] offset:2048
	global_load_dwordx4 v[48:51], v100, s[6:7] offset:3072
	s_add_u32 s6, s6, 0x800000
	s_addc_u32 s7, s7, 0
	s_waitcnt vmcnt(16)
	v_pk_mul_f32 v[68:69], v[52:53], v[52:53]
	v_pk_fma_f32 v[68:69], v[54:55], v[54:55], v[68:69]
	v_pk_fma_f32 v[68:69], v[56:57], v[56:57], v[68:69]
	v_pk_fma_f32 v[68:69], v[58:59], v[58:59], v[68:69]
	v_pk_fma_f32 v[68:69], v[60:61], v[60:61], v[68:69]
	v_pk_fma_f32 v[68:69], v[62:63], v[62:63], v[68:69]
	v_pk_fma_f32 v[68:69], v[64:65], v[64:65], v[68:69]
	v_pk_fma_f32 v[68:69], v[66:67], v[66:67], v[68:69]
	v_add_f32_e32 v70, v68, v69
	s_nop 1
	v_add_f32_dpp v71, v70, v70 quad_perm:[1,0,3,2] row_mask:0xf bank_mask:0xf
	s_nop 1
	v_add_f32_dpp v70, v71, v71 quad_perm:[2,3,0,1] row_mask:0xf bank_mask:0xf
	s_nop 1
	v_add_f32_dpp v71, v70, v70 row_half_mirror row_mask:0xf bank_mask:0xf
	s_nop 1
	v_add_f32_dpp v70, v71, v71 row_mirror row_mask:0xf bank_mask:0xf
	v_mov_b32_e32 v71, v70
	s_nop 1
	v_add_f32_dpp v71, v70, v70 row_bcast:15 row_mask:0xa bank_mask:0xf
	s_nop 1
	v_mov_b32_e32 v70, v71
	s_nop 1
	v_add_f32_dpp v70, v71, v71 row_bcast:31 row_mask:0xc bank_mask:0xf
	s_nop 1
	v_readlane_b32 s16, v70, 63
	s_nop 1
	v_mov_b32_e32 v72, s16
	v_fmamk_f32 v72, v72, 0x3a800000, v74
	v_rsq_f32_e32 v72, v72
	s_nop 0
	v_pk_mul_f32 v[52:53], v[52:53], v[72:73] op_sel_hi:[1,0]
	v_pk_mul_f32 v[54:55], v[54:55], v[72:73] op_sel_hi:[1,0]
	v_pk_mul_f32 v[52:53], v[52:53], v[0:1]
	v_pk_mul_f32 v[54:55], v[54:55], v[2:3]
	global_store_dwordx4 v100, v[52:55], s[8:9]
	v_pk_mul_f32 v[56:57], v[56:57], v[72:73] op_sel_hi:[1,0]
	v_pk_mul_f32 v[58:59], v[58:59], v[72:73] op_sel_hi:[1,0]
	v_pk_mul_f32 v[56:57], v[56:57], v[4:5]
	v_pk_mul_f32 v[58:59], v[58:59], v[6:7]
	global_store_dwordx4 v100, v[56:59], s[8:9] offset:1024
	v_pk_mul_f32 v[60:61], v[60:61], v[72:73] op_sel_hi:[1,0]
	v_pk_mul_f32 v[62:63], v[62:63], v[72:73] op_sel_hi:[1,0]
	v_pk_mul_f32 v[60:61], v[60:61], v[8:9]
	v_pk_mul_f32 v[62:63], v[62:63], v[10:11]
	global_store_dwordx4 v100, v[60:63], s[8:9] offset:2048
	v_pk_mul_f32 v[64:65], v[64:65], v[72:73] op_sel_hi:[1,0]
	v_pk_mul_f32 v[66:67], v[66:67], v[72:73] op_sel_hi:[1,0]
	v_pk_mul_f32 v[64:65], v[64:65], v[12:13]
	v_pk_mul_f32 v[66:67], v[66:67], v[14:15]
	global_store_dwordx4 v100, v[64:67], s[8:9] offset:3072
	s_add_u32 s8, s8, 0x800000
	s_addc_u32 s9, s9, 0
	global_load_dwordx4 v[52:55], v100, s[6:7]
	global_load_dwordx4 v[56:59], v100, s[6:7] offset:1024
	global_load_dwordx4 v[60:63], v100, s[6:7] offset:2048
	global_load_dwordx4 v[64:67], v100, s[6:7] offset:3072
	s_add_u32 s6, s6, 0x800000
	s_addc_u32 s7, s7, 0
	s_waitcnt vmcnt(16)
	v_pk_mul_f32 v[68:69], v[20:21], v[20:21]
	v_pk_fma_f32 v[68:69], v[22:23], v[22:23], v[68:69]
	v_pk_fma_f32 v[68:69], v[24:25], v[24:25], v[68:69]
	v_pk_fma_f32 v[68:69], v[26:27], v[26:27], v[68:69]
	v_pk_fma_f32 v[68:69], v[28:29], v[28:29], v[68:69]
	v_pk_fma_f32 v[68:69], v[30:31], v[30:31], v[68:69]
	v_pk_fma_f32 v[68:69], v[32:33], v[32:33], v[68:69]
	v_pk_fma_f32 v[68:69], v[34:35], v[34:35], v[68:69]
	v_add_f32_e32 v70, v68, v69
	s_nop 1
	v_add_f32_dpp v71, v70, v70 quad_perm:[1,0,3,2] row_mask:0xf bank_mask:0xf
	s_nop 1
	v_add_f32_dpp v70, v71, v71 quad_perm:[2,3,0,1] row_mask:0xf bank_mask:0xf
	s_nop 1
	v_add_f32_dpp v71, v70, v70 row_half_mirror row_mask:0xf bank_mask:0xf
	s_nop 1
	v_add_f32_dpp v70, v71, v71 row_mirror row_mask:0xf bank_mask:0xf
	v_mov_b32_e32 v71, v70
	s_nop 1
	v_add_f32_dpp v71, v70, v70 row_bcast:15 row_mask:0xa bank_mask:0xf
	s_nop 1
	v_mov_b32_e32 v70, v71
	s_nop 1
	v_add_f32_dpp v70, v71, v71 row_bcast:31 row_mask:0xc bank_mask:0xf
	s_nop 1
	v_readlane_b32 s16, v70, 63
	s_nop 1
	v_mov_b32_e32 v72, s16
	v_fmamk_f32 v72, v72, 0x3a800000, v74
	v_rsq_f32_e32 v72, v72
	s_nop 0
	v_pk_mul_f32 v[20:21], v[20:21], v[72:73] op_sel_hi:[1,0]
	v_pk_mul_f32 v[22:23], v[22:23], v[72:73] op_sel_hi:[1,0]
	v_pk_mul_f32 v[20:21], v[20:21], v[0:1]
	v_pk_mul_f32 v[22:23], v[22:23], v[2:3]
	global_store_dwordx4 v100, v[20:23], s[8:9]
	v_pk_mul_f32 v[24:25], v[24:25], v[72:73] op_sel_hi:[1,0]
	v_pk_mul_f32 v[26:27], v[26:27], v[72:73] op_sel_hi:[1,0]
	v_pk_mul_f32 v[24:25], v[24:25], v[4:5]
	v_pk_mul_f32 v[26:27], v[26:27], v[6:7]
	global_store_dwordx4 v100, v[24:27], s[8:9] offset:1024
	v_pk_mul_f32 v[28:29], v[28:29], v[72:73] op_sel_hi:[1,0]
	v_pk_mul_f32 v[30:31], v[30:31], v[72:73] op_sel_hi:[1,0]
	v_pk_mul_f32 v[28:29], v[28:29], v[8:9]
	v_pk_mul_f32 v[30:31], v[30:31], v[10:11]
	global_store_dwordx4 v100, v[28:31], s[8:9] offset:2048
	v_pk_mul_f32 v[32:33], v[32:33], v[72:73] op_sel_hi:[1,0]
	v_pk_mul_f32 v[34:35], v[34:35], v[72:73] op_sel_hi:[1,0]
	v_pk_mul_f32 v[32:33], v[32:33], v[12:13]
	v_pk_mul_f32 v[34:35], v[34:35], v[14:15]
	global_store_dwordx4 v100, v[32:35], s[8:9] offset:3072
	s_add_u32 s8, s8, 0x800000
	s_addc_u32 s9, s9, 0
	global_load_dwordx4 v[20:23], v100, s[6:7]
	global_load_dwordx4 v[24:27], v100, s[6:7] offset:1024
	global_load_dwordx4 v[28:31], v100, s[6:7] offset:2048
	global_load_dwordx4 v[32:35], v100, s[6:7] offset:3072
	s_add_u32 s6, s6, 0x800000
	s_addc_u32 s7, s7, 0
	s_waitcnt vmcnt(16)
	v_pk_mul_f32 v[68:69], v[36:37], v[36:37]
	v_pk_fma_f32 v[68:69], v[38:39], v[38:39], v[68:69]
	v_pk_fma_f32 v[68:69], v[40:41], v[40:41], v[68:69]
	v_pk_fma_f32 v[68:69], v[42:43], v[42:43], v[68:69]
	v_pk_fma_f32 v[68:69], v[44:45], v[44:45], v[68:69]
	v_pk_fma_f32 v[68:69], v[46:47], v[46:47], v[68:69]
	v_pk_fma_f32 v[68:69], v[48:49], v[48:49], v[68:69]
	v_pk_fma_f32 v[68:69], v[50:51], v[50:51], v[68:69]
	v_add_f32_e32 v70, v68, v69
	s_nop 1
	v_add_f32_dpp v71, v70, v70 quad_perm:[1,0,3,2] row_mask:0xf bank_mask:0xf
	s_nop 1
	v_add_f32_dpp v70, v71, v71 quad_perm:[2,3,0,1] row_mask:0xf bank_mask:0xf
	s_nop 1
	v_add_f32_dpp v71, v70, v70 row_half_mirror row_mask:0xf bank_mask:0xf
	s_nop 1
	v_add_f32_dpp v70, v71, v71 row_mirror row_mask:0xf bank_mask:0xf
	v_mov_b32_e32 v71, v70
	s_nop 1
	v_add_f32_dpp v71, v70, v70 row_bcast:15 row_mask:0xa bank_mask:0xf
	s_nop 1
	v_mov_b32_e32 v70, v71
	s_nop 1
	v_add_f32_dpp v70, v71, v71 row_bcast:31 row_mask:0xc bank_mask:0xf
	s_nop 1
	v_readlane_b32 s16, v70, 63
	s_nop 1
	v_mov_b32_e32 v72, s16
	v_fmamk_f32 v72, v72, 0x3a800000, v74
	v_rsq_f32_e32 v72, v72
	s_nop 0
	v_pk_mul_f32 v[36:37], v[36:37], v[72:73] op_sel_hi:[1,0]
	v_pk_mul_f32 v[38:39], v[38:39], v[72:73] op_sel_hi:[1,0]
	v_pk_mul_f32 v[36:37], v[36:37], v[0:1]
	v_pk_mul_f32 v[38:39], v[38:39], v[2:3]
	global_store_dwordx4 v100, v[36:39], s[8:9]
	v_pk_mul_f32 v[40:41], v[40:41], v[72:73] op_sel_hi:[1,0]
	v_pk_mul_f32 v[42:43], v[42:43], v[72:73] op_sel_hi:[1,0]
	v_pk_mul_f32 v[40:41], v[40:41], v[4:5]
	v_pk_mul_f32 v[42:43], v[42:43], v[6:7]
	global_store_dwordx4 v100, v[40:43], s[8:9] offset:1024
	v_pk_mul_f32 v[44:45], v[44:45], v[72:73] op_sel_hi:[1,0]
	v_pk_mul_f32 v[46:47], v[46:47], v[72:73] op_sel_hi:[1,0]
	v_pk_mul_f32 v[44:45], v[44:45], v[8:9]
	v_pk_mul_f32 v[46:47], v[46:47], v[10:11]
	global_store_dwordx4 v100, v[44:47], s[8:9] offset:2048
	v_pk_mul_f32 v[48:49], v[48:49], v[72:73] op_sel_hi:[1,0]
	v_pk_mul_f32 v[50:51], v[50:51], v[72:73] op_sel_hi:[1,0]
	v_pk_mul_f32 v[48:49], v[48:49], v[12:13]
	v_pk_mul_f32 v[50:51], v[50:51], v[14:15]
	global_store_dwordx4 v100, v[48:51], s[8:9] offset:3072
	s_add_u32 s8, s8, 0x800000
	s_addc_u32 s9, s9, 0
	global_load_dwordx4 v[36:39], v100, s[6:7]
	global_load_dwordx4 v[40:43], v100, s[6:7] offset:1024
	global_load_dwordx4 v[44:47], v100, s[6:7] offset:2048
	global_load_dwordx4 v[48:51], v100, s[6:7] offset:3072
	s_add_u32 s6, s6, 0x800000
	s_addc_u32 s7, s7, 0
	s_waitcnt vmcnt(16)
	v_pk_mul_f32 v[68:69], v[52:53], v[52:53]
	v_pk_fma_f32 v[68:69], v[54:55], v[54:55], v[68:69]
	v_pk_fma_f32 v[68:69], v[56:57], v[56:57], v[68:69]
	v_pk_fma_f32 v[68:69], v[58:59], v[58:59], v[68:69]
	v_pk_fma_f32 v[68:69], v[60:61], v[60:61], v[68:69]
	v_pk_fma_f32 v[68:69], v[62:63], v[62:63], v[68:69]
	v_pk_fma_f32 v[68:69], v[64:65], v[64:65], v[68:69]
	v_pk_fma_f32 v[68:69], v[66:67], v[66:67], v[68:69]
	v_add_f32_e32 v70, v68, v69
	s_nop 1
	v_add_f32_dpp v71, v70, v70 quad_perm:[1,0,3,2] row_mask:0xf bank_mask:0xf
	s_nop 1
	v_add_f32_dpp v70, v71, v71 quad_perm:[2,3,0,1] row_mask:0xf bank_mask:0xf
	s_nop 1
	v_add_f32_dpp v71, v70, v70 row_half_mirror row_mask:0xf bank_mask:0xf
	s_nop 1
	v_add_f32_dpp v70, v71, v71 row_mirror row_mask:0xf bank_mask:0xf
	v_mov_b32_e32 v71, v70
	s_nop 1
	v_add_f32_dpp v71, v70, v70 row_bcast:15 row_mask:0xa bank_mask:0xf
	s_nop 1
	v_mov_b32_e32 v70, v71
	s_nop 1
	v_add_f32_dpp v70, v71, v71 row_bcast:31 row_mask:0xc bank_mask:0xf
	s_nop 1
	v_readlane_b32 s16, v70, 63
	s_nop 1
	v_mov_b32_e32 v72, s16
	v_fmamk_f32 v72, v72, 0x3a800000, v74
	v_rsq_f32_e32 v72, v72
	s_nop 0
	v_pk_mul_f32 v[52:53], v[52:53], v[72:73] op_sel_hi:[1,0]
	v_pk_mul_f32 v[54:55], v[54:55], v[72:73] op_sel_hi:[1,0]
	v_pk_mul_f32 v[52:53], v[52:53], v[0:1]
	v_pk_mul_f32 v[54:55], v[54:55], v[2:3]
	global_store_dwordx4 v100, v[52:55], s[8:9]
	v_pk_mul_f32 v[56:57], v[56:57], v[72:73] op_sel_hi:[1,0]
	v_pk_mul_f32 v[58:59], v[58:59], v[72:73] op_sel_hi:[1,0]
	v_pk_mul_f32 v[56:57], v[56:57], v[4:5]
	v_pk_mul_f32 v[58:59], v[58:59], v[6:7]
	global_store_dwordx4 v100, v[56:59], s[8:9] offset:1024
	v_pk_mul_f32 v[60:61], v[60:61], v[72:73] op_sel_hi:[1,0]
	v_pk_mul_f32 v[62:63], v[62:63], v[72:73] op_sel_hi:[1,0]
	v_pk_mul_f32 v[60:61], v[60:61], v[8:9]
	v_pk_mul_f32 v[62:63], v[62:63], v[10:11]
	global_store_dwordx4 v100, v[60:63], s[8:9] offset:2048
	v_pk_mul_f32 v[64:65], v[64:65], v[72:73] op_sel_hi:[1,0]
	v_pk_mul_f32 v[66:67], v[66:67], v[72:73] op_sel_hi:[1,0]
	v_pk_mul_f32 v[64:65], v[64:65], v[12:13]
	v_pk_mul_f32 v[66:67], v[66:67], v[14:15]
	global_store_dwordx4 v100, v[64:67], s[8:9] offset:3072
	s_add_u32 s8, s8, 0x800000
	s_addc_u32 s9, s9, 0
	global_load_dwordx4 v[52:55], v100, s[6:7]
	global_load_dwordx4 v[56:59], v100, s[6:7] offset:1024
	global_load_dwordx4 v[60:63], v100, s[6:7] offset:2048
	global_load_dwordx4 v[64:67], v100, s[6:7] offset:3072
	s_add_u32 s6, s6, 0x800000
	s_addc_u32 s7, s7, 0
	s_waitcnt vmcnt(16)
	v_pk_mul_f32 v[68:69], v[20:21], v[20:21]
	v_pk_fma_f32 v[68:69], v[22:23], v[22:23], v[68:69]
	v_pk_fma_f32 v[68:69], v[24:25], v[24:25], v[68:69]
	v_pk_fma_f32 v[68:69], v[26:27], v[26:27], v[68:69]
	v_pk_fma_f32 v[68:69], v[28:29], v[28:29], v[68:69]
	v_pk_fma_f32 v[68:69], v[30:31], v[30:31], v[68:69]
	v_pk_fma_f32 v[68:69], v[32:33], v[32:33], v[68:69]
	v_pk_fma_f32 v[68:69], v[34:35], v[34:35], v[68:69]
	v_add_f32_e32 v70, v68, v69
	s_nop 1
	v_add_f32_dpp v71, v70, v70 quad_perm:[1,0,3,2] row_mask:0xf bank_mask:0xf
	s_nop 1
	v_add_f32_dpp v70, v71, v71 quad_perm:[2,3,0,1] row_mask:0xf bank_mask:0xf
	s_nop 1
	v_add_f32_dpp v71, v70, v70 row_half_mirror row_mask:0xf bank_mask:0xf
	s_nop 1
	v_add_f32_dpp v70, v71, v71 row_mirror row_mask:0xf bank_mask:0xf
	v_mov_b32_e32 v71, v70
	s_nop 1
	v_add_f32_dpp v71, v70, v70 row_bcast:15 row_mask:0xa bank_mask:0xf
	s_nop 1
	v_mov_b32_e32 v70, v71
	s_nop 1
	v_add_f32_dpp v70, v71, v71 row_bcast:31 row_mask:0xc bank_mask:0xf
	s_nop 1
	v_readlane_b32 s16, v70, 63
	s_nop 1
	v_mov_b32_e32 v72, s16
	v_fmamk_f32 v72, v72, 0x3a800000, v74
	v_rsq_f32_e32 v72, v72
	s_nop 0
	v_pk_mul_f32 v[20:21], v[20:21], v[72:73] op_sel_hi:[1,0]
	v_pk_mul_f32 v[22:23], v[22:23], v[72:73] op_sel_hi:[1,0]
	v_pk_mul_f32 v[20:21], v[20:21], v[0:1]
	v_pk_mul_f32 v[22:23], v[22:23], v[2:3]
	global_store_dwordx4 v100, v[20:23], s[8:9]
	v_pk_mul_f32 v[24:25], v[24:25], v[72:73] op_sel_hi:[1,0]
	v_pk_mul_f32 v[26:27], v[26:27], v[72:73] op_sel_hi:[1,0]
	v_pk_mul_f32 v[24:25], v[24:25], v[4:5]
	v_pk_mul_f32 v[26:27], v[26:27], v[6:7]
	global_store_dwordx4 v100, v[24:27], s[8:9] offset:1024
	v_pk_mul_f32 v[28:29], v[28:29], v[72:73] op_sel_hi:[1,0]
	v_pk_mul_f32 v[30:31], v[30:31], v[72:73] op_sel_hi:[1,0]
	v_pk_mul_f32 v[28:29], v[28:29], v[8:9]
	v_pk_mul_f32 v[30:31], v[30:31], v[10:11]
	global_store_dwordx4 v100, v[28:31], s[8:9] offset:2048
	v_pk_mul_f32 v[32:33], v[32:33], v[72:73] op_sel_hi:[1,0]
	v_pk_mul_f32 v[34:35], v[34:35], v[72:73] op_sel_hi:[1,0]
	v_pk_mul_f32 v[32:33], v[32:33], v[12:13]
	v_pk_mul_f32 v[34:35], v[34:35], v[14:15]
	global_store_dwordx4 v100, v[32:35], s[8:9] offset:3072
	s_add_u32 s8, s8, 0x800000
	s_addc_u32 s9, s9, 0
	global_load_dwordx4 v[20:23], v100, s[6:7]
	global_load_dwordx4 v[24:27], v100, s[6:7] offset:1024
	global_load_dwordx4 v[28:31], v100, s[6:7] offset:2048
	global_load_dwordx4 v[32:35], v100, s[6:7] offset:3072
	s_add_u32 s6, s6, 0x800000
	s_addc_u32 s7, s7, 0
	s_waitcnt vmcnt(16)
	v_pk_mul_f32 v[68:69], v[36:37], v[36:37]
	v_pk_fma_f32 v[68:69], v[38:39], v[38:39], v[68:69]
	v_pk_fma_f32 v[68:69], v[40:41], v[40:41], v[68:69]
	v_pk_fma_f32 v[68:69], v[42:43], v[42:43], v[68:69]
	v_pk_fma_f32 v[68:69], v[44:45], v[44:45], v[68:69]
	v_pk_fma_f32 v[68:69], v[46:47], v[46:47], v[68:69]
	v_pk_fma_f32 v[68:69], v[48:49], v[48:49], v[68:69]
	v_pk_fma_f32 v[68:69], v[50:51], v[50:51], v[68:69]
	v_add_f32_e32 v70, v68, v69
	s_nop 1
	v_add_f32_dpp v71, v70, v70 quad_perm:[1,0,3,2] row_mask:0xf bank_mask:0xf
	s_nop 1
	v_add_f32_dpp v70, v71, v71 quad_perm:[2,3,0,1] row_mask:0xf bank_mask:0xf
	s_nop 1
	v_add_f32_dpp v71, v70, v70 row_half_mirror row_mask:0xf bank_mask:0xf
	s_nop 1
	v_add_f32_dpp v70, v71, v71 row_mirror row_mask:0xf bank_mask:0xf
	v_mov_b32_e32 v71, v70
	s_nop 1
	v_add_f32_dpp v71, v70, v70 row_bcast:15 row_mask:0xa bank_mask:0xf
	s_nop 1
	v_mov_b32_e32 v70, v71
	s_nop 1
	v_add_f32_dpp v70, v71, v71 row_bcast:31 row_mask:0xc bank_mask:0xf
	s_nop 1
	v_readlane_b32 s16, v70, 63
	s_nop 1
	v_mov_b32_e32 v72, s16
	v_fmamk_f32 v72, v72, 0x3a800000, v74
	v_rsq_f32_e32 v72, v72
	s_nop 0
	v_pk_mul_f32 v[36:37], v[36:37], v[72:73] op_sel_hi:[1,0]
	v_pk_mul_f32 v[38:39], v[38:39], v[72:73] op_sel_hi:[1,0]
	v_pk_mul_f32 v[36:37], v[36:37], v[0:1]
	v_pk_mul_f32 v[38:39], v[38:39], v[2:3]
	global_store_dwordx4 v100, v[36:39], s[8:9]
	v_pk_mul_f32 v[40:41], v[40:41], v[72:73] op_sel_hi:[1,0]
	v_pk_mul_f32 v[42:43], v[42:43], v[72:73] op_sel_hi:[1,0]
	v_pk_mul_f32 v[40:41], v[40:41], v[4:5]
	v_pk_mul_f32 v[42:43], v[42:43], v[6:7]
	global_store_dwordx4 v100, v[40:43], s[8:9] offset:1024
	v_pk_mul_f32 v[44:45], v[44:45], v[72:73] op_sel_hi:[1,0]
	v_pk_mul_f32 v[46:47], v[46:47], v[72:73] op_sel_hi:[1,0]
	v_pk_mul_f32 v[44:45], v[44:45], v[8:9]
	v_pk_mul_f32 v[46:47], v[46:47], v[10:11]
	global_store_dwordx4 v100, v[44:47], s[8:9] offset:2048
	v_pk_mul_f32 v[48:49], v[48:49], v[72:73] op_sel_hi:[1,0]
	v_pk_mul_f32 v[50:51], v[50:51], v[72:73] op_sel_hi:[1,0]
	v_pk_mul_f32 v[48:49], v[48:49], v[12:13]
	v_pk_mul_f32 v[50:51], v[50:51], v[14:15]
	global_store_dwordx4 v100, v[48:51], s[8:9] offset:3072
	s_add_u32 s8, s8, 0x800000
	s_addc_u32 s9, s9, 0
	global_load_dwordx4 v[36:39], v100, s[6:7]
	global_load_dwordx4 v[40:43], v100, s[6:7] offset:1024
	global_load_dwordx4 v[44:47], v100, s[6:7] offset:2048
	global_load_dwordx4 v[48:51], v100, s[6:7] offset:3072
	s_add_u32 s6, s6, 0x800000
	s_addc_u32 s7, s7, 0
	s_waitcnt vmcnt(16)
	v_pk_mul_f32 v[68:69], v[52:53], v[52:53]
	v_pk_fma_f32 v[68:69], v[54:55], v[54:55], v[68:69]
	v_pk_fma_f32 v[68:69], v[56:57], v[56:57], v[68:69]
	v_pk_fma_f32 v[68:69], v[58:59], v[58:59], v[68:69]
	v_pk_fma_f32 v[68:69], v[60:61], v[60:61], v[68:69]
	v_pk_fma_f32 v[68:69], v[62:63], v[62:63], v[68:69]
	v_pk_fma_f32 v[68:69], v[64:65], v[64:65], v[68:69]
	v_pk_fma_f32 v[68:69], v[66:67], v[66:67], v[68:69]
	v_add_f32_e32 v70, v68, v69
	s_nop 1
	v_add_f32_dpp v71, v70, v70 quad_perm:[1,0,3,2] row_mask:0xf bank_mask:0xf
	s_nop 1
	v_add_f32_dpp v70, v71, v71 quad_perm:[2,3,0,1] row_mask:0xf bank_mask:0xf
	s_nop 1
	v_add_f32_dpp v71, v70, v70 row_half_mirror row_mask:0xf bank_mask:0xf
	s_nop 1
	v_add_f32_dpp v70, v71, v71 row_mirror row_mask:0xf bank_mask:0xf
	v_mov_b32_e32 v71, v70
	s_nop 1
	v_add_f32_dpp v71, v70, v70 row_bcast:15 row_mask:0xa bank_mask:0xf
	s_nop 1
	v_mov_b32_e32 v70, v71
	s_nop 1
	v_add_f32_dpp v70, v71, v71 row_bcast:31 row_mask:0xc bank_mask:0xf
	s_nop 1
	v_readlane_b32 s16, v70, 63
	s_nop 1
	v_mov_b32_e32 v72, s16
	v_fmamk_f32 v72, v72, 0x3a800000, v74
	v_rsq_f32_e32 v72, v72
	s_nop 0
	v_pk_mul_f32 v[52:53], v[52:53], v[72:73] op_sel_hi:[1,0]
	v_pk_mul_f32 v[54:55], v[54:55], v[72:73] op_sel_hi:[1,0]
	v_pk_mul_f32 v[52:53], v[52:53], v[0:1]
	v_pk_mul_f32 v[54:55], v[54:55], v[2:3]
	global_store_dwordx4 v100, v[52:55], s[8:9]
	v_pk_mul_f32 v[56:57], v[56:57], v[72:73] op_sel_hi:[1,0]
	v_pk_mul_f32 v[58:59], v[58:59], v[72:73] op_sel_hi:[1,0]
	v_pk_mul_f32 v[56:57], v[56:57], v[4:5]
	v_pk_mul_f32 v[58:59], v[58:59], v[6:7]
	global_store_dwordx4 v100, v[56:59], s[8:9] offset:1024
	v_pk_mul_f32 v[60:61], v[60:61], v[72:73] op_sel_hi:[1,0]
	v_pk_mul_f32 v[62:63], v[62:63], v[72:73] op_sel_hi:[1,0]
	v_pk_mul_f32 v[60:61], v[60:61], v[8:9]
	v_pk_mul_f32 v[62:63], v[62:63], v[10:11]
	global_store_dwordx4 v100, v[60:63], s[8:9] offset:2048
	v_pk_mul_f32 v[64:65], v[64:65], v[72:73] op_sel_hi:[1,0]
	v_pk_mul_f32 v[66:67], v[66:67], v[72:73] op_sel_hi:[1,0]
	v_pk_mul_f32 v[64:65], v[64:65], v[12:13]
	v_pk_mul_f32 v[66:67], v[66:67], v[14:15]
	global_store_dwordx4 v100, v[64:67], s[8:9] offset:3072
	s_add_u32 s8, s8, 0x800000
	s_addc_u32 s9, s9, 0
	global_load_dwordx4 v[52:55], v100, s[6:7]
	global_load_dwordx4 v[56:59], v100, s[6:7] offset:1024
	global_load_dwordx4 v[60:63], v100, s[6:7] offset:2048
	global_load_dwordx4 v[64:67], v100, s[6:7] offset:3072
	s_add_u32 s6, s6, 0x800000
	s_addc_u32 s7, s7, 0
	s_waitcnt vmcnt(16)
	v_pk_mul_f32 v[68:69], v[20:21], v[20:21]
	v_pk_fma_f32 v[68:69], v[22:23], v[22:23], v[68:69]
	v_pk_fma_f32 v[68:69], v[24:25], v[24:25], v[68:69]
	v_pk_fma_f32 v[68:69], v[26:27], v[26:27], v[68:69]
	v_pk_fma_f32 v[68:69], v[28:29], v[28:29], v[68:69]
	v_pk_fma_f32 v[68:69], v[30:31], v[30:31], v[68:69]
	v_pk_fma_f32 v[68:69], v[32:33], v[32:33], v[68:69]
	v_pk_fma_f32 v[68:69], v[34:35], v[34:35], v[68:69]
	v_add_f32_e32 v70, v68, v69
	s_nop 1
	v_add_f32_dpp v71, v70, v70 quad_perm:[1,0,3,2] row_mask:0xf bank_mask:0xf
	s_nop 1
	v_add_f32_dpp v70, v71, v71 quad_perm:[2,3,0,1] row_mask:0xf bank_mask:0xf
	s_nop 1
	v_add_f32_dpp v71, v70, v70 row_half_mirror row_mask:0xf bank_mask:0xf
	s_nop 1
	v_add_f32_dpp v70, v71, v71 row_mirror row_mask:0xf bank_mask:0xf
	v_mov_b32_e32 v71, v70
	s_nop 1
	v_add_f32_dpp v71, v70, v70 row_bcast:15 row_mask:0xa bank_mask:0xf
	s_nop 1
	v_mov_b32_e32 v70, v71
	s_nop 1
	v_add_f32_dpp v70, v71, v71 row_bcast:31 row_mask:0xc bank_mask:0xf
	s_nop 1
	v_readlane_b32 s16, v70, 63
	s_nop 1
	v_mov_b32_e32 v72, s16
	v_fmamk_f32 v72, v72, 0x3a800000, v74
	v_rsq_f32_e32 v72, v72
	s_nop 0
	v_pk_mul_f32 v[20:21], v[20:21], v[72:73] op_sel_hi:[1,0]
	v_pk_mul_f32 v[22:23], v[22:23], v[72:73] op_sel_hi:[1,0]
	v_pk_mul_f32 v[20:21], v[20:21], v[0:1]
	v_pk_mul_f32 v[22:23], v[22:23], v[2:3]
	global_store_dwordx4 v100, v[20:23], s[8:9]
	v_pk_mul_f32 v[24:25], v[24:25], v[72:73] op_sel_hi:[1,0]
	v_pk_mul_f32 v[26:27], v[26:27], v[72:73] op_sel_hi:[1,0]
	v_pk_mul_f32 v[24:25], v[24:25], v[4:5]
	v_pk_mul_f32 v[26:27], v[26:27], v[6:7]
	global_store_dwordx4 v100, v[24:27], s[8:9] offset:1024
	v_pk_mul_f32 v[28:29], v[28:29], v[72:73] op_sel_hi:[1,0]
	v_pk_mul_f32 v[30:31], v[30:31], v[72:73] op_sel_hi:[1,0]
	v_pk_mul_f32 v[28:29], v[28:29], v[8:9]
	v_pk_mul_f32 v[30:31], v[30:31], v[10:11]
	global_store_dwordx4 v100, v[28:31], s[8:9] offset:2048
	v_pk_mul_f32 v[32:33], v[32:33], v[72:73] op_sel_hi:[1,0]
	v_pk_mul_f32 v[34:35], v[34:35], v[72:73] op_sel_hi:[1,0]
	v_pk_mul_f32 v[32:33], v[32:33], v[12:13]
	v_pk_mul_f32 v[34:35], v[34:35], v[14:15]
	global_store_dwordx4 v100, v[32:35], s[8:9] offset:3072
	s_add_u32 s8, s8, 0x800000
	s_addc_u32 s9, s9, 0
	global_load_dwordx4 v[20:23], v100, s[6:7]
	global_load_dwordx4 v[24:27], v100, s[6:7] offset:1024
	global_load_dwordx4 v[28:31], v100, s[6:7] offset:2048
	global_load_dwordx4 v[32:35], v100, s[6:7] offset:3072
	s_add_u32 s6, s6, 0x800000
	s_addc_u32 s7, s7, 0
	s_waitcnt vmcnt(16)
	v_pk_mul_f32 v[68:69], v[36:37], v[36:37]
	v_pk_fma_f32 v[68:69], v[38:39], v[38:39], v[68:69]
	v_pk_fma_f32 v[68:69], v[40:41], v[40:41], v[68:69]
	v_pk_fma_f32 v[68:69], v[42:43], v[42:43], v[68:69]
	v_pk_fma_f32 v[68:69], v[44:45], v[44:45], v[68:69]
	v_pk_fma_f32 v[68:69], v[46:47], v[46:47], v[68:69]
	v_pk_fma_f32 v[68:69], v[48:49], v[48:49], v[68:69]
	v_pk_fma_f32 v[68:69], v[50:51], v[50:51], v[68:69]
	v_add_f32_e32 v70, v68, v69
	s_nop 1
	v_add_f32_dpp v71, v70, v70 quad_perm:[1,0,3,2] row_mask:0xf bank_mask:0xf
	s_nop 1
	v_add_f32_dpp v70, v71, v71 quad_perm:[2,3,0,1] row_mask:0xf bank_mask:0xf
	s_nop 1
	v_add_f32_dpp v71, v70, v70 row_half_mirror row_mask:0xf bank_mask:0xf
	s_nop 1
	v_add_f32_dpp v70, v71, v71 row_mirror row_mask:0xf bank_mask:0xf
	v_mov_b32_e32 v71, v70
	s_nop 1
	v_add_f32_dpp v71, v70, v70 row_bcast:15 row_mask:0xa bank_mask:0xf
	s_nop 1
	v_mov_b32_e32 v70, v71
	s_nop 1
	v_add_f32_dpp v70, v71, v71 row_bcast:31 row_mask:0xc bank_mask:0xf
	s_nop 1
	v_readlane_b32 s16, v70, 63
	s_nop 1
	v_mov_b32_e32 v72, s16
	v_fmamk_f32 v72, v72, 0x3a800000, v74
	v_rsq_f32_e32 v72, v72
	s_nop 0
	v_pk_mul_f32 v[36:37], v[36:37], v[72:73] op_sel_hi:[1,0]
	v_pk_mul_f32 v[38:39], v[38:39], v[72:73] op_sel_hi:[1,0]
	v_pk_mul_f32 v[36:37], v[36:37], v[0:1]
	v_pk_mul_f32 v[38:39], v[38:39], v[2:3]
	global_store_dwordx4 v100, v[36:39], s[8:9]
	v_pk_mul_f32 v[40:41], v[40:41], v[72:73] op_sel_hi:[1,0]
	v_pk_mul_f32 v[42:43], v[42:43], v[72:73] op_sel_hi:[1,0]
	v_pk_mul_f32 v[40:41], v[40:41], v[4:5]
	v_pk_mul_f32 v[42:43], v[42:43], v[6:7]
	global_store_dwordx4 v100, v[40:43], s[8:9] offset:1024
	v_pk_mul_f32 v[44:45], v[44:45], v[72:73] op_sel_hi:[1,0]
	v_pk_mul_f32 v[46:47], v[46:47], v[72:73] op_sel_hi:[1,0]
	v_pk_mul_f32 v[44:45], v[44:45], v[8:9]
	v_pk_mul_f32 v[46:47], v[46:47], v[10:11]
	global_store_dwordx4 v100, v[44:47], s[8:9] offset:2048
	v_pk_mul_f32 v[48:49], v[48:49], v[72:73] op_sel_hi:[1,0]
	v_pk_mul_f32 v[50:51], v[50:51], v[72:73] op_sel_hi:[1,0]
	v_pk_mul_f32 v[48:49], v[48:49], v[12:13]
	v_pk_mul_f32 v[50:51], v[50:51], v[14:15]
	global_store_dwordx4 v100, v[48:51], s[8:9] offset:3072
	s_add_u32 s8, s8, 0x800000
	s_addc_u32 s9, s9, 0
	s_waitcnt vmcnt(12)
	v_pk_mul_f32 v[68:69], v[52:53], v[52:53]
	v_pk_fma_f32 v[68:69], v[54:55], v[54:55], v[68:69]
	v_pk_fma_f32 v[68:69], v[56:57], v[56:57], v[68:69]
	v_pk_fma_f32 v[68:69], v[58:59], v[58:59], v[68:69]
	v_pk_fma_f32 v[68:69], v[60:61], v[60:61], v[68:69]
	v_pk_fma_f32 v[68:69], v[62:63], v[62:63], v[68:69]
	v_pk_fma_f32 v[68:69], v[64:65], v[64:65], v[68:69]
	v_pk_fma_f32 v[68:69], v[66:67], v[66:67], v[68:69]
	v_add_f32_e32 v70, v68, v69
	s_nop 1
	v_add_f32_dpp v71, v70, v70 quad_perm:[1,0,3,2] row_mask:0xf bank_mask:0xf
	s_nop 1
	v_add_f32_dpp v70, v71, v71 quad_perm:[2,3,0,1] row_mask:0xf bank_mask:0xf
	s_nop 1
	v_add_f32_dpp v71, v70, v70 row_half_mirror row_mask:0xf bank_mask:0xf
	s_nop 1
	v_add_f32_dpp v70, v71, v71 row_mirror row_mask:0xf bank_mask:0xf
	v_mov_b32_e32 v71, v70
	s_nop 1
	v_add_f32_dpp v71, v70, v70 row_bcast:15 row_mask:0xa bank_mask:0xf
	s_nop 1
	v_mov_b32_e32 v70, v71
	s_nop 1
	v_add_f32_dpp v70, v71, v71 row_bcast:31 row_mask:0xc bank_mask:0xf
	s_nop 1
	v_readlane_b32 s16, v70, 63
	s_nop 1
	v_mov_b32_e32 v72, s16
	v_fmamk_f32 v72, v72, 0x3a800000, v74
	v_rsq_f32_e32 v72, v72
	s_nop 0
	v_pk_mul_f32 v[52:53], v[52:53], v[72:73] op_sel_hi:[1,0]
	v_pk_mul_f32 v[54:55], v[54:55], v[72:73] op_sel_hi:[1,0]
	v_pk_mul_f32 v[52:53], v[52:53], v[0:1]
	v_pk_mul_f32 v[54:55], v[54:55], v[2:3]
	global_store_dwordx4 v100, v[52:55], s[8:9]
	v_pk_mul_f32 v[56:57], v[56:57], v[72:73] op_sel_hi:[1,0]
	v_pk_mul_f32 v[58:59], v[58:59], v[72:73] op_sel_hi:[1,0]
	v_pk_mul_f32 v[56:57], v[56:57], v[4:5]
	v_pk_mul_f32 v[58:59], v[58:59], v[6:7]
	global_store_dwordx4 v100, v[56:59], s[8:9] offset:1024
	v_pk_mul_f32 v[60:61], v[60:61], v[72:73] op_sel_hi:[1,0]
	v_pk_mul_f32 v[62:63], v[62:63], v[72:73] op_sel_hi:[1,0]
	v_pk_mul_f32 v[60:61], v[60:61], v[8:9]
	v_pk_mul_f32 v[62:63], v[62:63], v[10:11]
	global_store_dwordx4 v100, v[60:63], s[8:9] offset:2048
	v_pk_mul_f32 v[64:65], v[64:65], v[72:73] op_sel_hi:[1,0]
	v_pk_mul_f32 v[66:67], v[66:67], v[72:73] op_sel_hi:[1,0]
	v_pk_mul_f32 v[64:65], v[64:65], v[12:13]
	v_pk_mul_f32 v[66:67], v[66:67], v[14:15]
	global_store_dwordx4 v100, v[64:67], s[8:9] offset:3072
	s_add_u32 s8, s8, 0x800000
	s_addc_u32 s9, s9, 0
	s_waitcnt vmcnt(8)
	v_pk_mul_f32 v[68:69], v[20:21], v[20:21]
	v_pk_fma_f32 v[68:69], v[22:23], v[22:23], v[68:69]
	v_pk_fma_f32 v[68:69], v[24:25], v[24:25], v[68:69]
	v_pk_fma_f32 v[68:69], v[26:27], v[26:27], v[68:69]
	v_pk_fma_f32 v[68:69], v[28:29], v[28:29], v[68:69]
	v_pk_fma_f32 v[68:69], v[30:31], v[30:31], v[68:69]
	v_pk_fma_f32 v[68:69], v[32:33], v[32:33], v[68:69]
	v_pk_fma_f32 v[68:69], v[34:35], v[34:35], v[68:69]
	v_add_f32_e32 v70, v68, v69
	s_nop 1
	v_add_f32_dpp v71, v70, v70 quad_perm:[1,0,3,2] row_mask:0xf bank_mask:0xf
	s_nop 1
	v_add_f32_dpp v70, v71, v71 quad_perm:[2,3,0,1] row_mask:0xf bank_mask:0xf
	s_nop 1
	v_add_f32_dpp v71, v70, v70 row_half_mirror row_mask:0xf bank_mask:0xf
	s_nop 1
	v_add_f32_dpp v70, v71, v71 row_mirror row_mask:0xf bank_mask:0xf
	v_mov_b32_e32 v71, v70
	s_nop 1
	v_add_f32_dpp v71, v70, v70 row_bcast:15 row_mask:0xa bank_mask:0xf
	s_nop 1
	v_mov_b32_e32 v70, v71
	s_nop 1
	v_add_f32_dpp v70, v71, v71 row_bcast:31 row_mask:0xc bank_mask:0xf
	s_nop 1
	v_readlane_b32 s16, v70, 63
	s_nop 1
	v_mov_b32_e32 v72, s16
	v_fmamk_f32 v72, v72, 0x3a800000, v74
	v_rsq_f32_e32 v72, v72
	s_nop 0
	v_pk_mul_f32 v[20:21], v[20:21], v[72:73] op_sel_hi:[1,0]
	v_pk_mul_f32 v[22:23], v[22:23], v[72:73] op_sel_hi:[1,0]
	v_pk_mul_f32 v[20:21], v[20:21], v[0:1]
	v_pk_mul_f32 v[22:23], v[22:23], v[2:3]
	global_store_dwordx4 v100, v[20:23], s[8:9]
	v_pk_mul_f32 v[24:25], v[24:25], v[72:73] op_sel_hi:[1,0]
	v_pk_mul_f32 v[26:27], v[26:27], v[72:73] op_sel_hi:[1,0]
	v_pk_mul_f32 v[24:25], v[24:25], v[4:5]
	v_pk_mul_f32 v[26:27], v[26:27], v[6:7]
	global_store_dwordx4 v100, v[24:27], s[8:9] offset:1024
	v_pk_mul_f32 v[28:29], v[28:29], v[72:73] op_sel_hi:[1,0]
	v_pk_mul_f32 v[30:31], v[30:31], v[72:73] op_sel_hi:[1,0]
	v_pk_mul_f32 v[28:29], v[28:29], v[8:9]
	v_pk_mul_f32 v[30:31], v[30:31], v[10:11]
	global_store_dwordx4 v100, v[28:31], s[8:9] offset:2048
	v_pk_mul_f32 v[32:33], v[32:33], v[72:73] op_sel_hi:[1,0]
	v_pk_mul_f32 v[34:35], v[34:35], v[72:73] op_sel_hi:[1,0]
	v_pk_mul_f32 v[32:33], v[32:33], v[12:13]
	v_pk_mul_f32 v[34:35], v[34:35], v[14:15]
	global_store_dwordx4 v100, v[32:35], s[8:9] offset:3072
